# GEMM K-loops: 12 of 16 stage loads per iteration issued as scalar base + 32-bit lane offset (no per-load 64-bit VALU add)
# speedup vs baseline: 1.0072x; 1.0072x over previous
.LBB0_397:
	s_add_u32 s42, s24, 0xfffc0080
	s_addc_u32 s43, s25, -1
	s_add_i32 s66, 0, 0x10000
	s_cmp_eq_u32 s65, 12
	s_cselect_b32 vcc_hi, s23, s43
	s_cselect_b32 vcc_lo, s26, s42
	s_cselect_b32 s43, s27, s45
	s_cselect_b32 s42, s28, s29
	s_add_i32 s83, 0, 0x14000
	v_add_u32_e32 v76, s66, v185
	v_add_u32_e32 v154, s83, v185
	ds_read_b128 v[64:67], v76
	ds_read_b128 v[68:71], v76 offset:1024
	ds_read_b128 v[72:75], v76 offset:2048
	ds_read_b128 v[76:79], v76 offset:3072
	ds_read_b128 v[144:147], v154
	ds_read_b128 v[148:151], v154 offset:1024
	ds_read_b128 v[172:175], v154 offset:2048
	ds_read_b128 v[176:179], v154 offset:3072
	s_add_i32 m0, s33, 0xc000
	ds_read_b128 v[180:183], v194
	ds_read_b128 v[196:199], v194 offset:1024
	ds_read_b128 v[200:203], v194 offset:2048
	ds_read_b128 v[204:207], v194 offset:3072
	ds_read_b128 v[208:211], v194 offset:4096
	ds_read_b128 v[212:215], v194 offset:5120
	ds_read_b128 v[216:219], v194 offset:6144
	ds_read_b128 v[220:223], v194 offset:7168
	global_load_lds_dwordx4 v168, s[24:25]
	s_add_i32 m0, s33, 0xe000
	s_nop 0
	global_load_lds_dwordx4 v170, s[24:25]
	s_waitcnt vmcnt(8)
	s_waitcnt lgkmcnt(0)
	s_barrier
	s_setprio 1
	s_waitcnt lgkmcnt(0)
	v_mfma_f32_16x16x32_bf16 v[140:143], v[64:67], v[180:183], v[140:143]
	v_mfma_f32_16x16x32_bf16 v[136:139], v[72:75], v[180:183], v[136:139]
	v_mfma_f32_16x16x32_bf16 v[124:127], v[64:67], v[200:203], v[124:127]
	v_mfma_f32_16x16x32_bf16 v[120:123], v[72:75], v[200:203], v[120:123]
	v_mfma_f32_16x16x32_bf16 v[108:111], v[64:67], v[208:211], v[108:111]
	v_mfma_f32_16x16x32_bf16 v[104:107], v[72:75], v[208:211], v[104:107]
	v_mfma_f32_16x16x32_bf16 v[92:95], v[64:67], v[216:219], v[92:95]
	v_mfma_f32_16x16x32_bf16 v[88:91], v[72:75], v[216:219], v[88:91]
	v_mfma_f32_16x16x32_bf16 v[140:143], v[68:71], v[196:199], v[140:143]
	v_mfma_f32_16x16x32_bf16 v[136:139], v[76:79], v[196:199], v[136:139]
	v_mfma_f32_16x16x32_bf16 v[124:127], v[68:71], v[204:207], v[124:127]
	v_mfma_f32_16x16x32_bf16 v[120:123], v[76:79], v[204:207], v[120:123]
	v_mfma_f32_16x16x32_bf16 v[108:111], v[68:71], v[212:215], v[108:111]
	v_mfma_f32_16x16x32_bf16 v[104:107], v[76:79], v[212:215], v[104:107]
	v_mfma_f32_16x16x32_bf16 v[92:95], v[68:71], v[220:223], v[92:95]
	v_mfma_f32_16x16x32_bf16 v[88:91], v[76:79], v[220:223], v[88:91]
	s_setprio 0
	s_setprio 1
	v_mfma_f32_16x16x32_bf16 v[132:135], v[144:147], v[180:183], v[132:135]
	v_mfma_f32_16x16x32_bf16 v[128:131], v[172:175], v[180:183], v[128:131]
	v_mfma_f32_16x16x32_bf16 v[116:119], v[144:147], v[200:203], v[116:119]
	v_mfma_f32_16x16x32_bf16 v[112:115], v[172:175], v[200:203], v[112:115]
	v_mfma_f32_16x16x32_bf16 v[100:103], v[144:147], v[208:211], v[100:103]
	v_mfma_f32_16x16x32_bf16 v[96:99], v[172:175], v[208:211], v[96:99]
	v_mfma_f32_16x16x32_bf16 v[84:87], v[144:147], v[216:219], v[84:87]
	v_mfma_f32_16x16x32_bf16 v[80:83], v[172:175], v[216:219], v[80:83]
	v_mfma_f32_16x16x32_bf16 v[132:135], v[148:151], v[196:199], v[132:135]
	v_mfma_f32_16x16x32_bf16 v[128:131], v[176:179], v[196:199], v[128:131]
	v_mfma_f32_16x16x32_bf16 v[116:119], v[148:151], v[204:207], v[116:119]
	v_mfma_f32_16x16x32_bf16 v[112:115], v[176:179], v[204:207], v[112:115]
	v_mfma_f32_16x16x32_bf16 v[100:103], v[148:151], v[212:215], v[100:103]
	v_mfma_f32_16x16x32_bf16 v[96:99], v[176:179], v[212:215], v[96:99]
	v_mfma_f32_16x16x32_bf16 v[84:87], v[148:151], v[220:223], v[84:87]
	v_mfma_f32_16x16x32_bf16 v[80:83], v[176:179], v[220:223], v[80:83]
	s_setprio 0
	s_barrier
	s_add_i32 s66, s66, s31
	v_lshl_add_u64 v[224:225], s[42:43], 0, v[152:153]
	s_mov_b32 m0, s66
	ds_read_b128 v[180:183], v194 offset:16384
	ds_read_b128 v[196:199], v194 offset:17408
	ds_read_b128 v[200:203], v194 offset:18432
	ds_read_b128 v[204:207], v194 offset:19456
	ds_read_b128 v[208:211], v194 offset:20480
	ds_read_b128 v[212:215], v194 offset:21504
	ds_read_b128 v[216:219], v194 offset:22528
	ds_read_b128 v[220:223], v194 offset:23552
	global_load_lds_dwordx4 v152, s[42:43]
	s_add_i32 m0, s66, 0x2000
	s_add_u32 s90, s42, 0x40000
	v_lshl_add_u64 v[226:227], s[42:43], 0, v[166:167]
	s_addc_u32 s91, s43, 0
	s_add_i32 s66, s83, s31
	global_load_lds_dwordx4 v166, s[42:43]
	s_mov_b32 m0, s66
	v_lshl_add_u64 v[230:231], vcc, 0, v[164:165]
	global_load_lds_dwordx4 v152, s[90:91]
	s_add_i32 m0, s66, 0x2000
	s_nop 0
	global_load_lds_dwordx4 v166, s[90:91]
	v_lshl_add_u64 v[228:229], vcc, 0, v[162:163]
	s_mov_b32 m0, s33
	s_nop 0
	global_load_lds_dwordx4 v162, vcc
	s_mov_b32 m0, s36
	s_nop 0
	global_load_lds_dwordx4 v164, vcc
	s_waitcnt vmcnt(8)
	s_waitcnt lgkmcnt(0)
	s_barrier
	s_setprio 1
	s_waitcnt lgkmcnt(0)
	v_mfma_f32_16x16x32_bf16 v[60:63], v[64:67], v[180:183], v[60:63]
	v_mfma_f32_16x16x32_bf16 v[56:59], v[72:75], v[180:183], v[56:59]
	v_mfma_f32_16x16x32_bf16 v[44:47], v[64:67], v[200:203], v[44:47]
	v_mfma_f32_16x16x32_bf16 v[40:43], v[72:75], v[200:203], v[40:43]
	v_mfma_f32_16x16x32_bf16 v[28:31], v[64:67], v[208:211], v[28:31]
	v_mfma_f32_16x16x32_bf16 v[24:27], v[72:75], v[208:211], v[24:27]
	v_mfma_f32_16x16x32_bf16 v[12:15], v[64:67], v[216:219], v[12:15]
	v_mfma_f32_16x16x32_bf16 v[8:11], v[72:75], v[216:219], v[8:11]
	v_mfma_f32_16x16x32_bf16 v[60:63], v[68:71], v[196:199], v[60:63]
	v_mfma_f32_16x16x32_bf16 v[56:59], v[76:79], v[196:199], v[56:59]
	v_mfma_f32_16x16x32_bf16 v[44:47], v[68:71], v[204:207], v[44:47]
	v_mfma_f32_16x16x32_bf16 v[40:43], v[76:79], v[204:207], v[40:43]
	v_mfma_f32_16x16x32_bf16 v[28:31], v[68:71], v[212:215], v[28:31]
	v_mfma_f32_16x16x32_bf16 v[24:27], v[76:79], v[212:215], v[24:27]
	v_mfma_f32_16x16x32_bf16 v[12:15], v[68:71], v[220:223], v[12:15]
	v_mfma_f32_16x16x32_bf16 v[8:11], v[76:79], v[220:223], v[8:11]
	s_setprio 0
	s_setprio 1
	v_mfma_f32_16x16x32_bf16 v[52:55], v[144:147], v[180:183], v[52:55]
	v_mfma_f32_16x16x32_bf16 v[48:51], v[172:175], v[180:183], v[48:51]
	v_mfma_f32_16x16x32_bf16 v[36:39], v[144:147], v[200:203], v[36:39]
	v_mfma_f32_16x16x32_bf16 v[32:35], v[172:175], v[200:203], v[32:35]
	v_mfma_f32_16x16x32_bf16 v[20:23], v[144:147], v[208:211], v[20:23]
	v_mfma_f32_16x16x32_bf16 v[16:19], v[172:175], v[208:211], v[16:19]
	v_mfma_f32_16x16x32_bf16 v[4:7], v[144:147], v[216:219], v[4:7]
	v_mfma_f32_16x16x32_bf16 v[0:3], v[172:175], v[216:219], v[0:3]
	v_mfma_f32_16x16x32_bf16 v[52:55], v[148:151], v[196:199], v[52:55]
	v_mfma_f32_16x16x32_bf16 v[48:51], v[176:179], v[196:199], v[48:51]
	v_mfma_f32_16x16x32_bf16 v[36:39], v[148:151], v[204:207], v[36:39]
	v_mfma_f32_16x16x32_bf16 v[32:35], v[176:179], v[204:207], v[32:35]
	v_mfma_f32_16x16x32_bf16 v[20:23], v[148:151], v[212:215], v[20:23]
	v_mfma_f32_16x16x32_bf16 v[16:19], v[176:179], v[212:215], v[16:19]
	v_mfma_f32_16x16x32_bf16 v[4:7], v[148:151], v[220:223], v[4:7]
	v_mfma_f32_16x16x32_bf16 v[0:3], v[176:179], v[220:223], v[0:3]
	s_setprio 0
	s_barrier
	s_add_i32 s66, 0, 0x18000
	s_add_i32 s83, 0, 0x1c000
	v_add_u32_e32 v76, s66, v185
	v_add_u32_e32 v154, s83, v185
	ds_read_b128 v[64:67], v76
	ds_read_b128 v[68:71], v76 offset:1024
	ds_read_b128 v[72:75], v76 offset:2048
	ds_read_b128 v[76:79], v76 offset:3072
	ds_read_b128 v[144:147], v154
	ds_read_b128 v[148:151], v154 offset:1024
	ds_read_b128 v[172:175], v154 offset:2048
	ds_read_b128 v[176:179], v154 offset:3072
	s_add_u32 s90, vcc_lo, 0x40000
	s_addc_u32 s91, vcc_hi, 0
	s_mov_b32 m0, s37
	ds_read_b128 v[180:183], v194 offset:32768
	ds_read_b128 v[196:199], v194 offset:33792
	ds_read_b128 v[200:203], v194 offset:34816
	ds_read_b128 v[204:207], v194 offset:35840
	ds_read_b128 v[208:211], v194 offset:36864
	ds_read_b128 v[212:215], v194 offset:37888
	ds_read_b128 v[216:219], v194 offset:38912
	ds_read_b128 v[220:223], v194 offset:39936
	global_load_lds_dwordx4 v162, s[90:91]
	s_mov_b32 m0, s60
	s_nop 0
	global_load_lds_dwordx4 v164, s[90:91]
	s_waitcnt vmcnt(8)
	s_waitcnt lgkmcnt(0)
	s_barrier
	s_setprio 1
	s_waitcnt lgkmcnt(0)
	v_mfma_f32_16x16x32_bf16 v[140:143], v[64:67], v[180:183], v[140:143]
	v_mfma_f32_16x16x32_bf16 v[136:139], v[72:75], v[180:183], v[136:139]
	v_mfma_f32_16x16x32_bf16 v[124:127], v[64:67], v[200:203], v[124:127]
	v_mfma_f32_16x16x32_bf16 v[120:123], v[72:75], v[200:203], v[120:123]
	v_mfma_f32_16x16x32_bf16 v[108:111], v[64:67], v[208:211], v[108:111]
	v_mfma_f32_16x16x32_bf16 v[104:107], v[72:75], v[208:211], v[104:107]
	v_mfma_f32_16x16x32_bf16 v[92:95], v[64:67], v[216:219], v[92:95]
	v_mfma_f32_16x16x32_bf16 v[88:91], v[72:75], v[216:219], v[88:91]
	v_mfma_f32_16x16x32_bf16 v[140:143], v[68:71], v[196:199], v[140:143]
	v_mfma_f32_16x16x32_bf16 v[136:139], v[76:79], v[196:199], v[136:139]
	v_mfma_f32_16x16x32_bf16 v[124:127], v[68:71], v[204:207], v[124:127]
	v_mfma_f32_16x16x32_bf16 v[120:123], v[76:79], v[204:207], v[120:123]
	v_mfma_f32_16x16x32_bf16 v[108:111], v[68:71], v[212:215], v[108:111]
	v_mfma_f32_16x16x32_bf16 v[104:107], v[76:79], v[212:215], v[104:107]
	v_mfma_f32_16x16x32_bf16 v[92:95], v[68:71], v[220:223], v[92:95]
	v_mfma_f32_16x16x32_bf16 v[88:91], v[76:79], v[220:223], v[88:91]
	s_setprio 0
	s_setprio 1
	v_mfma_f32_16x16x32_bf16 v[132:135], v[144:147], v[180:183], v[132:135]
	v_mfma_f32_16x16x32_bf16 v[128:131], v[172:175], v[180:183], v[128:131]
	v_mfma_f32_16x16x32_bf16 v[116:119], v[144:147], v[200:203], v[116:119]
	v_mfma_f32_16x16x32_bf16 v[112:115], v[172:175], v[200:203], v[112:115]
	v_mfma_f32_16x16x32_bf16 v[100:103], v[144:147], v[208:211], v[100:103]
	v_mfma_f32_16x16x32_bf16 v[96:99], v[172:175], v[208:211], v[96:99]
	v_mfma_f32_16x16x32_bf16 v[84:87], v[144:147], v[216:219], v[84:87]
	v_mfma_f32_16x16x32_bf16 v[80:83], v[172:175], v[216:219], v[80:83]
	v_mfma_f32_16x16x32_bf16 v[132:135], v[148:151], v[196:199], v[132:135]
	v_mfma_f32_16x16x32_bf16 v[128:131], v[176:179], v[196:199], v[128:131]
	v_mfma_f32_16x16x32_bf16 v[116:119], v[148:151], v[204:207], v[116:119]
	v_mfma_f32_16x16x32_bf16 v[112:115], v[176:179], v[204:207], v[112:115]
	v_mfma_f32_16x16x32_bf16 v[100:103], v[148:151], v[212:215], v[100:103]
	v_mfma_f32_16x16x32_bf16 v[96:99], v[176:179], v[212:215], v[96:99]
	v_mfma_f32_16x16x32_bf16 v[84:87], v[148:151], v[220:223], v[84:87]
	v_mfma_f32_16x16x32_bf16 v[80:83], v[176:179], v[220:223], v[80:83]
	s_setprio 0
	s_barrier
	s_add_i32 s66, s66, s31
	v_lshl_add_u64 v[224:225], v[224:225], 0, s[70:71]
	s_mov_b32 m0, s66
	ds_read_b128 v[180:183], v194 offset:49152
	ds_read_b128 v[196:199], v194 offset:50176
	ds_read_b128 v[200:203], v194 offset:51200
	ds_read_b128 v[204:207], v194 offset:52224
	ds_read_b128 v[208:211], v194 offset:53248
	ds_read_b128 v[212:215], v194 offset:54272
	ds_read_b128 v[216:219], v194 offset:55296
	ds_read_b128 v[220:223], v194 offset:56320
	global_load_lds_dwordx4 v[224:225], off
	s_add_i32 m0, s66, 0x2000
	s_add_u32 s42, s42, 0x40080
	v_lshl_add_u64 v[224:225], v[226:227], 0, s[70:71]
	s_addc_u32 s43, s43, 0
	s_add_i32 s66, s83, s31
	global_load_lds_dwordx4 v[224:225], off
	s_mov_b32 m0, s66
	s_nop 0
	global_load_lds_dwordx4 v152, s[42:43]
	s_add_i32 m0, s66, 0x2000
	s_nop 0
	global_load_lds_dwordx4 v166, s[42:43]
	v_lshl_add_u64 v[224:225], v[228:229], 0, s[70:71]
	s_mov_b32 m0, s75
	s_nop 0
	global_load_lds_dwordx4 v[224:225], off
	v_lshl_add_u64 v[224:225], v[230:231], 0, s[70:71]
	s_mov_b32 m0, s76
	s_nop 0
	global_load_lds_dwordx4 v[224:225], off
	s_waitcnt vmcnt(8)
	s_waitcnt lgkmcnt(0)
	s_barrier
	s_setprio 1
	s_waitcnt lgkmcnt(0)
	v_mfma_f32_16x16x32_bf16 v[60:63], v[64:67], v[180:183], v[60:63]
	v_mfma_f32_16x16x32_bf16 v[56:59], v[72:75], v[180:183], v[56:59]
	v_mfma_f32_16x16x32_bf16 v[44:47], v[64:67], v[200:203], v[44:47]
	v_mfma_f32_16x16x32_bf16 v[40:43], v[72:75], v[200:203], v[40:43]
	v_mfma_f32_16x16x32_bf16 v[28:31], v[64:67], v[208:211], v[28:31]
	v_mfma_f32_16x16x32_bf16 v[24:27], v[72:75], v[208:211], v[24:27]
	v_mfma_f32_16x16x32_bf16 v[12:15], v[64:67], v[216:219], v[12:15]
	v_mfma_f32_16x16x32_bf16 v[8:11], v[72:75], v[216:219], v[8:11]
	v_mfma_f32_16x16x32_bf16 v[60:63], v[68:71], v[196:199], v[60:63]
	v_mfma_f32_16x16x32_bf16 v[56:59], v[76:79], v[196:199], v[56:59]
	v_mfma_f32_16x16x32_bf16 v[44:47], v[68:71], v[204:207], v[44:47]
	v_mfma_f32_16x16x32_bf16 v[40:43], v[76:79], v[204:207], v[40:43]
	v_mfma_f32_16x16x32_bf16 v[28:31], v[68:71], v[212:215], v[28:31]
	v_mfma_f32_16x16x32_bf16 v[24:27], v[76:79], v[212:215], v[24:27]
	v_mfma_f32_16x16x32_bf16 v[12:15], v[68:71], v[220:223], v[12:15]
	v_mfma_f32_16x16x32_bf16 v[8:11], v[76:79], v[220:223], v[8:11]
	s_setprio 0
	s_setprio 1
	v_mfma_f32_16x16x32_bf16 v[52:55], v[144:147], v[180:183], v[52:55]
	v_mfma_f32_16x16x32_bf16 v[48:51], v[172:175], v[180:183], v[48:51]
	v_mfma_f32_16x16x32_bf16 v[36:39], v[144:147], v[200:203], v[36:39]
	v_mfma_f32_16x16x32_bf16 v[32:35], v[172:175], v[200:203], v[32:35]
	v_mfma_f32_16x16x32_bf16 v[20:23], v[144:147], v[208:211], v[20:23]
	v_mfma_f32_16x16x32_bf16 v[16:19], v[172:175], v[208:211], v[16:19]
	v_mfma_f32_16x16x32_bf16 v[4:7], v[144:147], v[216:219], v[4:7]
	v_mfma_f32_16x16x32_bf16 v[0:3], v[172:175], v[216:219], v[0:3]
	v_mfma_f32_16x16x32_bf16 v[52:55], v[148:151], v[196:199], v[52:55]
	v_mfma_f32_16x16x32_bf16 v[48:51], v[176:179], v[196:199], v[48:51]
	v_mfma_f32_16x16x32_bf16 v[36:39], v[148:151], v[204:207], v[36:39]
	v_mfma_f32_16x16x32_bf16 v[32:35], v[176:179], v[204:207], v[32:35]
	v_mfma_f32_16x16x32_bf16 v[20:23], v[148:151], v[212:215], v[20:23]
	v_mfma_f32_16x16x32_bf16 v[16:19], v[176:179], v[212:215], v[16:19]
	v_mfma_f32_16x16x32_bf16 v[4:7], v[148:151], v[220:223], v[4:7]
	v_mfma_f32_16x16x32_bf16 v[0:3], v[176:179], v[220:223], v[0:3]
	s_setprio 0
	s_barrier
	s_add_i32 s65, s65, 2
	s_add_u32 s24, s24, 0x100
	s_addc_u32 s25, s25, 0
	s_add_u32 s29, s29, 0x100
	s_addc_u32 s45, s45, 0
	s_cmp_gt_u32 s65, 13
	s_cbranch_scc0 .LBB0_397
	s_and_b64 vcc, exec, s[14:15]
	s_cbranch_vccz .LBB0_400
	s_barrier

.LBB0_559:
	s_add_u32 s63, s44, 0xfffc0080
	s_addc_u32 s64, s45, -1
	s_add_i32 s66, 0, 0x10000
	s_cmp_eq_u32 s62, 12
	s_cselect_b32 vcc_hi, s19, s64
	s_cselect_b32 vcc_lo, s23, s63
	s_cselect_b32 s65, s15, s61
	s_cselect_b32 s64, s43, s60
	s_add_i32 s63, 0, 0x14000
	v_add_u32_e32 v124, s66, v169
	v_add_u32_e32 v154, s63, v169
	ds_read_b128 v[112:115], v124
	ds_read_b128 v[116:119], v124 offset:1024
	ds_read_b128 v[120:123], v124 offset:2048
	ds_read_b128 v[124:127], v124 offset:3072
	ds_read_b128 v[164:167], v154
	ds_read_b128 v[172:175], v154 offset:1024
	ds_read_b128 v[176:179], v154 offset:2048
	ds_read_b128 v[180:183], v154 offset:3072
	s_add_i32 m0, s25, 0xc000
	ds_read_b128 v[184:187], v171
	ds_read_b128 v[188:191], v171 offset:1024
	ds_read_b128 v[192:195], v171 offset:2048
	ds_read_b128 v[196:199], v171 offset:3072
	ds_read_b128 v[200:203], v171 offset:4096
	ds_read_b128 v[204:207], v171 offset:5120
	ds_read_b128 v[208:211], v171 offset:6144
	ds_read_b128 v[212:215], v171 offset:7168
	global_load_lds_dwordx4 v150, s[44:45]
	s_add_i32 m0, s25, 0xe000
	s_nop 0
	global_load_lds_dwordx4 v162, s[44:45]
	s_waitcnt vmcnt(8)
	s_waitcnt lgkmcnt(0)
	s_barrier
	s_setprio 1
	s_waitcnt lgkmcnt(0)
	v_mfma_f32_16x16x32_bf16 v[140:143], v[112:115], v[184:187], v[140:143]
	v_mfma_f32_16x16x32_bf16 v[136:139], v[120:123], v[184:187], v[136:139]
	v_mfma_f32_16x16x32_bf16 v[108:111], v[112:115], v[192:195], v[108:111]
	v_mfma_f32_16x16x32_bf16 v[104:107], v[120:123], v[192:195], v[104:107]
	v_mfma_f32_16x16x32_bf16 v[92:95], v[112:115], v[200:203], v[92:95]
	v_mfma_f32_16x16x32_bf16 v[88:91], v[120:123], v[200:203], v[88:91]
	v_mfma_f32_16x16x32_bf16 v[76:79], v[112:115], v[208:211], v[76:79]
	v_mfma_f32_16x16x32_bf16 v[72:75], v[120:123], v[208:211], v[72:75]
	v_mfma_f32_16x16x32_bf16 v[140:143], v[116:119], v[188:191], v[140:143]
	v_mfma_f32_16x16x32_bf16 v[136:139], v[124:127], v[188:191], v[136:139]
	v_mfma_f32_16x16x32_bf16 v[108:111], v[116:119], v[196:199], v[108:111]
	v_mfma_f32_16x16x32_bf16 v[104:107], v[124:127], v[196:199], v[104:107]
	v_mfma_f32_16x16x32_bf16 v[92:95], v[116:119], v[204:207], v[92:95]
	v_mfma_f32_16x16x32_bf16 v[88:91], v[124:127], v[204:207], v[88:91]
	v_mfma_f32_16x16x32_bf16 v[76:79], v[116:119], v[212:215], v[76:79]
	v_mfma_f32_16x16x32_bf16 v[72:75], v[124:127], v[212:215], v[72:75]
	s_setprio 0
	s_setprio 1
	v_mfma_f32_16x16x32_bf16 v[132:135], v[164:167], v[184:187], v[132:135]
	v_mfma_f32_16x16x32_bf16 v[128:131], v[176:179], v[184:187], v[128:131]
	v_mfma_f32_16x16x32_bf16 v[100:103], v[164:167], v[192:195], v[100:103]
	v_mfma_f32_16x16x32_bf16 v[96:99], v[176:179], v[192:195], v[96:99]
	v_mfma_f32_16x16x32_bf16 v[84:87], v[164:167], v[200:203], v[84:87]
	v_mfma_f32_16x16x32_bf16 v[80:83], v[176:179], v[200:203], v[80:83]
	v_mfma_f32_16x16x32_bf16 v[68:71], v[164:167], v[208:211], v[68:71]
	v_mfma_f32_16x16x32_bf16 v[64:67], v[176:179], v[208:211], v[64:67]
	v_mfma_f32_16x16x32_bf16 v[132:135], v[172:175], v[188:191], v[132:135]
	v_mfma_f32_16x16x32_bf16 v[128:131], v[180:183], v[188:191], v[128:131]
	v_mfma_f32_16x16x32_bf16 v[100:103], v[172:175], v[196:199], v[100:103]
	v_mfma_f32_16x16x32_bf16 v[96:99], v[180:183], v[196:199], v[96:99]
	v_mfma_f32_16x16x32_bf16 v[84:87], v[172:175], v[204:207], v[84:87]
	v_mfma_f32_16x16x32_bf16 v[80:83], v[180:183], v[204:207], v[80:83]
	v_mfma_f32_16x16x32_bf16 v[68:71], v[172:175], v[212:215], v[68:71]
	v_mfma_f32_16x16x32_bf16 v[64:67], v[180:183], v[212:215], v[64:67]
	s_setprio 0
	s_barrier
	s_add_i32 s66, s66, s27
	v_lshl_add_u64 v[216:217], s[64:65], 0, v[152:153]
	s_mov_b32 m0, s66
	ds_read_b128 v[184:187], v171 offset:16384
	ds_read_b128 v[188:191], v171 offset:17408
	ds_read_b128 v[192:195], v171 offset:18432
	ds_read_b128 v[196:199], v171 offset:19456
	ds_read_b128 v[200:203], v171 offset:20480
	ds_read_b128 v[204:207], v171 offset:21504
	ds_read_b128 v[208:211], v171 offset:22528
	ds_read_b128 v[212:215], v171 offset:23552
	global_load_lds_dwordx4 v152, s[64:65]
	s_add_i32 m0, s66, 0x2000
	s_add_u32 s68, s64, 0x40000
	v_lshl_add_u64 v[218:219], s[64:65], 0, v[148:149]
	s_addc_u32 s69, s65, 0
	s_add_i32 s63, s63, s27
	global_load_lds_dwordx4 v148, s[64:65]
	s_mov_b32 m0, s63
	v_lshl_add_u64 v[222:223], vcc, 0, v[146:147]
	global_load_lds_dwordx4 v152, s[68:69]
	s_add_i32 m0, s63, 0x2000
	s_nop 0
	global_load_lds_dwordx4 v148, s[68:69]
	v_lshl_add_u64 v[220:221], vcc, 0, v[144:145]
	s_mov_b32 m0, s25
	s_nop 0
	global_load_lds_dwordx4 v144, vcc
	s_mov_b32 m0, s28
	s_nop 0
	global_load_lds_dwordx4 v146, vcc
	s_waitcnt vmcnt(8)
	s_waitcnt lgkmcnt(0)
	s_barrier
	s_setprio 1
	s_waitcnt lgkmcnt(0)
	v_mfma_f32_16x16x32_bf16 v[60:63], v[112:115], v[184:187], v[60:63]
	v_mfma_f32_16x16x32_bf16 v[56:59], v[120:123], v[184:187], v[56:59]
	v_mfma_f32_16x16x32_bf16 v[44:47], v[112:115], v[192:195], v[44:47]
	v_mfma_f32_16x16x32_bf16 v[40:43], v[120:123], v[192:195], v[40:43]
	v_mfma_f32_16x16x32_bf16 v[28:31], v[112:115], v[200:203], v[28:31]
	v_mfma_f32_16x16x32_bf16 v[24:27], v[120:123], v[200:203], v[24:27]
	v_mfma_f32_16x16x32_bf16 v[12:15], v[112:115], v[208:211], v[12:15]
	v_mfma_f32_16x16x32_bf16 v[8:11], v[120:123], v[208:211], v[8:11]
	v_mfma_f32_16x16x32_bf16 v[60:63], v[116:119], v[188:191], v[60:63]
	v_mfma_f32_16x16x32_bf16 v[56:59], v[124:127], v[188:191], v[56:59]
	v_mfma_f32_16x16x32_bf16 v[44:47], v[116:119], v[196:199], v[44:47]
	v_mfma_f32_16x16x32_bf16 v[40:43], v[124:127], v[196:199], v[40:43]
	v_mfma_f32_16x16x32_bf16 v[28:31], v[116:119], v[204:207], v[28:31]
	v_mfma_f32_16x16x32_bf16 v[24:27], v[124:127], v[204:207], v[24:27]
	v_mfma_f32_16x16x32_bf16 v[12:15], v[116:119], v[212:215], v[12:15]
	v_mfma_f32_16x16x32_bf16 v[8:11], v[124:127], v[212:215], v[8:11]
	s_setprio 0
	s_setprio 1
	v_mfma_f32_16x16x32_bf16 v[52:55], v[164:167], v[184:187], v[52:55]
	v_mfma_f32_16x16x32_bf16 v[48:51], v[176:179], v[184:187], v[48:51]
	v_mfma_f32_16x16x32_bf16 v[36:39], v[164:167], v[192:195], v[36:39]
	v_mfma_f32_16x16x32_bf16 v[32:35], v[176:179], v[192:195], v[32:35]
	v_mfma_f32_16x16x32_bf16 v[20:23], v[164:167], v[200:203], v[20:23]
	v_mfma_f32_16x16x32_bf16 v[16:19], v[176:179], v[200:203], v[16:19]
	v_mfma_f32_16x16x32_bf16 v[4:7], v[164:167], v[208:211], v[4:7]
	v_mfma_f32_16x16x32_bf16 v[0:3], v[176:179], v[208:211], v[0:3]
	v_mfma_f32_16x16x32_bf16 v[52:55], v[172:175], v[188:191], v[52:55]
	v_mfma_f32_16x16x32_bf16 v[48:51], v[180:183], v[188:191], v[48:51]
	v_mfma_f32_16x16x32_bf16 v[36:39], v[172:175], v[196:199], v[36:39]
	v_mfma_f32_16x16x32_bf16 v[32:35], v[180:183], v[196:199], v[32:35]
	v_mfma_f32_16x16x32_bf16 v[20:23], v[172:175], v[204:207], v[20:23]
	v_mfma_f32_16x16x32_bf16 v[16:19], v[180:183], v[204:207], v[16:19]
	v_mfma_f32_16x16x32_bf16 v[4:7], v[172:175], v[212:215], v[4:7]
	v_mfma_f32_16x16x32_bf16 v[0:3], v[180:183], v[212:215], v[0:3]
	s_setprio 0
	s_barrier
	s_add_i32 s63, 0, 0x18000
	s_add_i32 s66, 0, 0x1c000
	v_add_u32_e32 v124, s63, v169
	v_add_u32_e32 v154, s66, v169
	ds_read_b128 v[112:115], v124
	ds_read_b128 v[116:119], v124 offset:1024
	ds_read_b128 v[120:123], v124 offset:2048
	ds_read_b128 v[124:127], v124 offset:3072
	ds_read_b128 v[164:167], v154
	ds_read_b128 v[172:175], v154 offset:1024
	ds_read_b128 v[176:179], v154 offset:2048
	ds_read_b128 v[180:183], v154 offset:3072
	s_add_u32 s68, vcc_lo, 0x40000
	s_addc_u32 s69, vcc_hi, 0
	s_mov_b32 m0, s29
	ds_read_b128 v[184:187], v171 offset:32768
	ds_read_b128 v[188:191], v171 offset:33792
	ds_read_b128 v[192:195], v171 offset:34816
	ds_read_b128 v[196:199], v171 offset:35840
	ds_read_b128 v[200:203], v171 offset:36864
	ds_read_b128 v[204:207], v171 offset:37888
	ds_read_b128 v[208:211], v171 offset:38912
	ds_read_b128 v[212:215], v171 offset:39936
	global_load_lds_dwordx4 v144, s[68:69]
	s_mov_b32 m0, s30
	s_nop 0
	global_load_lds_dwordx4 v146, s[68:69]
	s_waitcnt vmcnt(8)
	s_waitcnt lgkmcnt(0)
	s_barrier
	s_setprio 1
	s_waitcnt lgkmcnt(0)
	v_mfma_f32_16x16x32_bf16 v[140:143], v[112:115], v[184:187], v[140:143]
	v_mfma_f32_16x16x32_bf16 v[136:139], v[120:123], v[184:187], v[136:139]
	v_mfma_f32_16x16x32_bf16 v[108:111], v[112:115], v[192:195], v[108:111]
	v_mfma_f32_16x16x32_bf16 v[104:107], v[120:123], v[192:195], v[104:107]
	v_mfma_f32_16x16x32_bf16 v[92:95], v[112:115], v[200:203], v[92:95]
	v_mfma_f32_16x16x32_bf16 v[88:91], v[120:123], v[200:203], v[88:91]
	v_mfma_f32_16x16x32_bf16 v[76:79], v[112:115], v[208:211], v[76:79]
	v_mfma_f32_16x16x32_bf16 v[72:75], v[120:123], v[208:211], v[72:75]
	v_mfma_f32_16x16x32_bf16 v[140:143], v[116:119], v[188:191], v[140:143]
	v_mfma_f32_16x16x32_bf16 v[136:139], v[124:127], v[188:191], v[136:139]
	v_mfma_f32_16x16x32_bf16 v[108:111], v[116:119], v[196:199], v[108:111]
	v_mfma_f32_16x16x32_bf16 v[104:107], v[124:127], v[196:199], v[104:107]
	v_mfma_f32_16x16x32_bf16 v[92:95], v[116:119], v[204:207], v[92:95]
	v_mfma_f32_16x16x32_bf16 v[88:91], v[124:127], v[204:207], v[88:91]
	v_mfma_f32_16x16x32_bf16 v[76:79], v[116:119], v[212:215], v[76:79]
	v_mfma_f32_16x16x32_bf16 v[72:75], v[124:127], v[212:215], v[72:75]
	s_setprio 0
	s_setprio 1
	v_mfma_f32_16x16x32_bf16 v[132:135], v[164:167], v[184:187], v[132:135]
	v_mfma_f32_16x16x32_bf16 v[128:131], v[176:179], v[184:187], v[128:131]
	v_mfma_f32_16x16x32_bf16 v[100:103], v[164:167], v[192:195], v[100:103]
	v_mfma_f32_16x16x32_bf16 v[96:99], v[176:179], v[192:195], v[96:99]
	v_mfma_f32_16x16x32_bf16 v[84:87], v[164:167], v[200:203], v[84:87]
	v_mfma_f32_16x16x32_bf16 v[80:83], v[176:179], v[200:203], v[80:83]
	v_mfma_f32_16x16x32_bf16 v[68:71], v[164:167], v[208:211], v[68:71]
	v_mfma_f32_16x16x32_bf16 v[64:67], v[176:179], v[208:211], v[64:67]
	v_mfma_f32_16x16x32_bf16 v[132:135], v[172:175], v[188:191], v[132:135]
	v_mfma_f32_16x16x32_bf16 v[128:131], v[180:183], v[188:191], v[128:131]
	v_mfma_f32_16x16x32_bf16 v[100:103], v[172:175], v[196:199], v[100:103]
	v_mfma_f32_16x16x32_bf16 v[96:99], v[180:183], v[196:199], v[96:99]
	v_mfma_f32_16x16x32_bf16 v[84:87], v[172:175], v[204:207], v[84:87]
	v_mfma_f32_16x16x32_bf16 v[80:83], v[180:183], v[204:207], v[80:83]
	v_mfma_f32_16x16x32_bf16 v[68:71], v[172:175], v[212:215], v[68:71]
	v_mfma_f32_16x16x32_bf16 v[64:67], v[180:183], v[212:215], v[64:67]
	s_setprio 0
	s_barrier
	s_add_i32 s63, s63, s27
	v_lshl_add_u64 v[216:217], v[216:217], 0, s[70:71]
	s_mov_b32 m0, s63
	ds_read_b128 v[184:187], v171 offset:49152
	ds_read_b128 v[188:191], v171 offset:50176
	ds_read_b128 v[192:195], v171 offset:51200
	ds_read_b128 v[196:199], v171 offset:52224
	ds_read_b128 v[200:203], v171 offset:53248
	ds_read_b128 v[204:207], v171 offset:54272
	ds_read_b128 v[208:211], v171 offset:55296
	ds_read_b128 v[212:215], v171 offset:56320
	global_load_lds_dwordx4 v[216:217], off
	s_add_i32 m0, s63, 0x2000
	s_add_u32 s64, s64, 0x40080
	v_lshl_add_u64 v[216:217], v[218:219], 0, s[70:71]
	s_addc_u32 s65, s65, 0
	s_add_i32 s63, s66, s27
	global_load_lds_dwordx4 v[216:217], off
	s_mov_b32 m0, s63
	s_nop 0
	global_load_lds_dwordx4 v152, s[64:65]
	s_add_i32 m0, s63, 0x2000
	s_nop 0
	global_load_lds_dwordx4 v148, s[64:65]
	v_lshl_add_u64 v[216:217], v[220:221], 0, s[70:71]
	s_mov_b32 m0, s33
	s_nop 0
	global_load_lds_dwordx4 v[216:217], off
	v_lshl_add_u64 v[216:217], v[222:223], 0, s[70:71]
	s_mov_b32 m0, s36
	s_nop 0
	global_load_lds_dwordx4 v[216:217], off
	s_waitcnt vmcnt(8)
	s_waitcnt lgkmcnt(0)
	s_barrier
	s_setprio 1
	s_waitcnt lgkmcnt(0)
	v_mfma_f32_16x16x32_bf16 v[60:63], v[112:115], v[184:187], v[60:63]
	v_mfma_f32_16x16x32_bf16 v[56:59], v[120:123], v[184:187], v[56:59]
	v_mfma_f32_16x16x32_bf16 v[44:47], v[112:115], v[192:195], v[44:47]
	v_mfma_f32_16x16x32_bf16 v[40:43], v[120:123], v[192:195], v[40:43]
	v_mfma_f32_16x16x32_bf16 v[28:31], v[112:115], v[200:203], v[28:31]
	v_mfma_f32_16x16x32_bf16 v[24:27], v[120:123], v[200:203], v[24:27]
	v_mfma_f32_16x16x32_bf16 v[12:15], v[112:115], v[208:211], v[12:15]
	v_mfma_f32_16x16x32_bf16 v[8:11], v[120:123], v[208:211], v[8:11]
	v_mfma_f32_16x16x32_bf16 v[60:63], v[116:119], v[188:191], v[60:63]
	v_mfma_f32_16x16x32_bf16 v[56:59], v[124:127], v[188:191], v[56:59]
	v_mfma_f32_16x16x32_bf16 v[44:47], v[116:119], v[196:199], v[44:47]
	v_mfma_f32_16x16x32_bf16 v[40:43], v[124:127], v[196:199], v[40:43]
	v_mfma_f32_16x16x32_bf16 v[28:31], v[116:119], v[204:207], v[28:31]
	v_mfma_f32_16x16x32_bf16 v[24:27], v[124:127], v[204:207], v[24:27]
	v_mfma_f32_16x16x32_bf16 v[12:15], v[116:119], v[212:215], v[12:15]
	v_mfma_f32_16x16x32_bf16 v[8:11], v[124:127], v[212:215], v[8:11]
	s_setprio 0
	s_setprio 1
	v_mfma_f32_16x16x32_bf16 v[52:55], v[164:167], v[184:187], v[52:55]
	v_mfma_f32_16x16x32_bf16 v[48:51], v[176:179], v[184:187], v[48:51]
	v_mfma_f32_16x16x32_bf16 v[36:39], v[164:167], v[192:195], v[36:39]
	v_mfma_f32_16x16x32_bf16 v[32:35], v[176:179], v[192:195], v[32:35]
	v_mfma_f32_16x16x32_bf16 v[20:23], v[164:167], v[200:203], v[20:23]
	v_mfma_f32_16x16x32_bf16 v[16:19], v[176:179], v[200:203], v[16:19]
	v_mfma_f32_16x16x32_bf16 v[4:7], v[164:167], v[208:211], v[4:7]
	v_mfma_f32_16x16x32_bf16 v[0:3], v[176:179], v[208:211], v[0:3]
	v_mfma_f32_16x16x32_bf16 v[52:55], v[172:175], v[188:191], v[52:55]
	v_mfma_f32_16x16x32_bf16 v[48:51], v[180:183], v[188:191], v[48:51]
	v_mfma_f32_16x16x32_bf16 v[36:39], v[172:175], v[196:199], v[36:39]
	v_mfma_f32_16x16x32_bf16 v[32:35], v[180:183], v[196:199], v[32:35]
	v_mfma_f32_16x16x32_bf16 v[20:23], v[172:175], v[204:207], v[20:23]
	v_mfma_f32_16x16x32_bf16 v[16:19], v[180:183], v[204:207], v[16:19]
	v_mfma_f32_16x16x32_bf16 v[4:7], v[172:175], v[212:215], v[4:7]
	v_mfma_f32_16x16x32_bf16 v[0:3], v[180:183], v[212:215], v[0:3]
	s_setprio 0
	s_barrier
	s_add_i32 s62, s62, 2
	s_add_u32 s44, s44, 0x100
	s_addc_u32 s45, s45, 0
	s_add_u32 s60, s60, 0x100
	s_addc_u32 s61, s61, 0
	s_cmp_gt_u32 s62, 13
	s_cbranch_scc0 .LBB0_559
	s_and_b64 vcc, exec, s[12:13]
	s_cbranch_vccz .LBB0_562
	s_barrier

.LBB0_635:
	s_add_u32 s12, s10, 0xfff00080
	s_addc_u32 s13, s11, -1
	s_add_i32 s27, 0, 0x10000
	s_cmp_eq_u32 s26, 60
	s_cselect_b32 s21, s19, s13
	s_cselect_b32 s20, s22, s12
	s_cselect_b32 s13, s17, s25
	s_cselect_b32 s12, s23, s24
	s_add_i32 s30, 0, 0x14000
	v_add_u32_e32 v100, s27, v249
	v_add_u32_e32 v154, s30, v249
	ds_read_b128 v[88:91], v100
	ds_read_b128 v[92:95], v100 offset:1024
	ds_read_b128 v[96:99], v100 offset:2048
	ds_read_b128 v[100:103], v100 offset:3072
	ds_read_b128 v[164:167], v154
	ds_read_b128 v[168:171], v154 offset:1024
	ds_read_b128 v[172:175], v154 offset:2048
	ds_read_b128 v[176:179], v154 offset:3072
	s_add_i32 m0, s60, 0xc000
	ds_read_b128 v[180:183], v251
	ds_read_b128 v[184:187], v251 offset:1024
	ds_read_b128 v[188:191], v251 offset:2048
	ds_read_b128 v[192:195], v251 offset:3072
	ds_read_b128 v[196:199], v251 offset:4096
	ds_read_b128 v[200:203], v251 offset:5120
	ds_read_b128 v[204:207], v251 offset:6144
	ds_read_b128 v[208:211], v251 offset:7168
	global_load_lds_dwordx4 v150, s[10:11]
	s_add_i32 m0, s60, 0xe000
	s_nop 0
	global_load_lds_dwordx4 v162, s[10:11]
	s_waitcnt vmcnt(8)
	s_waitcnt lgkmcnt(0)
	s_barrier
	s_setprio 1
	s_waitcnt lgkmcnt(0)
	v_mfma_f32_16x16x32_bf16 v[140:143], v[88:91], v[180:183], v[140:143]
	v_mfma_f32_16x16x32_bf16 v[136:139], v[96:99], v[180:183], v[136:139]
	v_mfma_f32_16x16x32_bf16 v[132:135], v[88:91], v[188:191], v[132:135]
	v_mfma_f32_16x16x32_bf16 v[128:131], v[96:99], v[188:191], v[128:131]
	v_mfma_f32_16x16x32_bf16 v[124:127], v[88:91], v[196:199], v[124:127]
	v_mfma_f32_16x16x32_bf16 v[120:123], v[96:99], v[196:199], v[120:123]
	v_mfma_f32_16x16x32_bf16 v[116:119], v[88:91], v[204:207], v[116:119]
	v_mfma_f32_16x16x32_bf16 v[112:115], v[96:99], v[204:207], v[112:115]
	v_mfma_f32_16x16x32_bf16 v[140:143], v[92:95], v[184:187], v[140:143]
	v_mfma_f32_16x16x32_bf16 v[136:139], v[100:103], v[184:187], v[136:139]
	v_mfma_f32_16x16x32_bf16 v[132:135], v[92:95], v[192:195], v[132:135]
	v_mfma_f32_16x16x32_bf16 v[128:131], v[100:103], v[192:195], v[128:131]
	v_mfma_f32_16x16x32_bf16 v[124:127], v[92:95], v[200:203], v[124:127]
	v_mfma_f32_16x16x32_bf16 v[120:123], v[100:103], v[200:203], v[120:123]
	v_mfma_f32_16x16x32_bf16 v[116:119], v[92:95], v[208:211], v[116:119]
	v_mfma_f32_16x16x32_bf16 v[112:115], v[100:103], v[208:211], v[112:115]
	s_setprio 0
	s_setprio 1
	v_mfma_f32_16x16x32_bf16 v[60:63], v[164:167], v[180:183], v[60:63]
	v_mfma_f32_16x16x32_bf16 v[56:59], v[172:175], v[180:183], v[56:59]
	v_mfma_f32_16x16x32_bf16 v[52:55], v[164:167], v[188:191], v[52:55]
	v_mfma_f32_16x16x32_bf16 v[48:51], v[172:175], v[188:191], v[48:51]
	v_mfma_f32_16x16x32_bf16 v[44:47], v[164:167], v[196:199], v[44:47]
	v_mfma_f32_16x16x32_bf16 v[40:43], v[172:175], v[196:199], v[40:43]
	v_mfma_f32_16x16x32_bf16 v[36:39], v[164:167], v[204:207], v[36:39]
	v_mfma_f32_16x16x32_bf16 v[32:35], v[172:175], v[204:207], v[32:35]
	v_mfma_f32_16x16x32_bf16 v[60:63], v[168:171], v[184:187], v[60:63]
	v_mfma_f32_16x16x32_bf16 v[56:59], v[176:179], v[184:187], v[56:59]
	v_mfma_f32_16x16x32_bf16 v[52:55], v[168:171], v[192:195], v[52:55]
	v_mfma_f32_16x16x32_bf16 v[48:51], v[176:179], v[192:195], v[48:51]
	v_mfma_f32_16x16x32_bf16 v[44:47], v[168:171], v[200:203], v[44:47]
	v_mfma_f32_16x16x32_bf16 v[40:43], v[176:179], v[200:203], v[40:43]
	v_mfma_f32_16x16x32_bf16 v[36:39], v[168:171], v[208:211], v[36:39]
	v_mfma_f32_16x16x32_bf16 v[32:35], v[176:179], v[208:211], v[32:35]
	s_setprio 0
	s_barrier
	s_add_i32 s27, s27, s62
	v_lshl_add_u64 v[212:213], s[12:13], 0, v[152:153]
	s_mov_b32 m0, s27
	ds_read_b128 v[180:183], v251 offset:16384
	ds_read_b128 v[184:187], v251 offset:17408
	ds_read_b128 v[188:191], v251 offset:18432
	ds_read_b128 v[192:195], v251 offset:19456
	ds_read_b128 v[196:199], v251 offset:20480
	ds_read_b128 v[200:203], v251 offset:21504
	ds_read_b128 v[204:207], v251 offset:22528
	ds_read_b128 v[208:211], v251 offset:23552
	global_load_lds_dwordx4 v152, s[12:13]
	s_add_i32 m0, s27, 0x2000
	s_add_u32 s28, s12, 0x100000
	v_lshl_add_u64 v[214:215], s[12:13], 0, v[148:149]
	s_addc_u32 s29, s13, 0
	s_add_i32 s27, s30, s62
	global_load_lds_dwordx4 v148, s[12:13]
	s_mov_b32 m0, s27
	v_lshl_add_u64 v[218:219], s[20:21], 0, v[146:147]
	global_load_lds_dwordx4 v152, s[28:29]
	s_add_i32 m0, s27, 0x2000
	s_nop 0
	global_load_lds_dwordx4 v148, s[28:29]
	v_lshl_add_u64 v[216:217], s[20:21], 0, v[144:145]
	s_mov_b32 m0, s60
	s_nop 0
	global_load_lds_dwordx4 v144, s[20:21]
	s_mov_b32 m0, s33
	s_nop 0
	global_load_lds_dwordx4 v146, s[20:21]
	s_waitcnt vmcnt(8)
	s_waitcnt lgkmcnt(0)
	s_barrier
	s_setprio 1
	s_waitcnt lgkmcnt(0)
	v_mfma_f32_16x16x32_bf16 v[108:111], v[88:91], v[180:183], v[108:111]
	v_mfma_f32_16x16x32_bf16 v[104:107], v[96:99], v[180:183], v[104:107]
	v_mfma_f32_16x16x32_bf16 v[84:87], v[88:91], v[188:191], v[84:87]
	v_mfma_f32_16x16x32_bf16 v[80:83], v[96:99], v[188:191], v[80:83]
	v_mfma_f32_16x16x32_bf16 v[76:79], v[88:91], v[196:199], v[76:79]
	v_mfma_f32_16x16x32_bf16 v[72:75], v[96:99], v[196:199], v[72:75]
	v_mfma_f32_16x16x32_bf16 v[68:71], v[88:91], v[204:207], v[68:71]
	v_mfma_f32_16x16x32_bf16 v[64:67], v[96:99], v[204:207], v[64:67]
	v_mfma_f32_16x16x32_bf16 v[108:111], v[92:95], v[184:187], v[108:111]
	v_mfma_f32_16x16x32_bf16 v[104:107], v[100:103], v[184:187], v[104:107]
	v_mfma_f32_16x16x32_bf16 v[84:87], v[92:95], v[192:195], v[84:87]
	v_mfma_f32_16x16x32_bf16 v[80:83], v[100:103], v[192:195], v[80:83]
	v_mfma_f32_16x16x32_bf16 v[76:79], v[92:95], v[200:203], v[76:79]
	v_mfma_f32_16x16x32_bf16 v[72:75], v[100:103], v[200:203], v[72:75]
	v_mfma_f32_16x16x32_bf16 v[68:71], v[92:95], v[208:211], v[68:71]
	v_mfma_f32_16x16x32_bf16 v[64:67], v[100:103], v[208:211], v[64:67]
	s_setprio 0
	s_setprio 1
	v_mfma_f32_16x16x32_bf16 v[28:31], v[164:167], v[180:183], v[28:31]
	v_mfma_f32_16x16x32_bf16 v[24:27], v[172:175], v[180:183], v[24:27]
	v_mfma_f32_16x16x32_bf16 v[20:23], v[164:167], v[188:191], v[20:23]
	v_mfma_f32_16x16x32_bf16 v[16:19], v[172:175], v[188:191], v[16:19]
	v_mfma_f32_16x16x32_bf16 v[12:15], v[164:167], v[196:199], v[12:15]
	v_mfma_f32_16x16x32_bf16 v[8:11], v[172:175], v[196:199], v[8:11]
	v_mfma_f32_16x16x32_bf16 v[4:7], v[164:167], v[204:207], v[4:7]
	v_mfma_f32_16x16x32_bf16 v[0:3], v[172:175], v[204:207], v[0:3]
	v_mfma_f32_16x16x32_bf16 v[28:31], v[168:171], v[184:187], v[28:31]
	v_mfma_f32_16x16x32_bf16 v[24:27], v[176:179], v[184:187], v[24:27]
	v_mfma_f32_16x16x32_bf16 v[20:23], v[168:171], v[192:195], v[20:23]
	v_mfma_f32_16x16x32_bf16 v[16:19], v[176:179], v[192:195], v[16:19]
	v_mfma_f32_16x16x32_bf16 v[12:15], v[168:171], v[200:203], v[12:15]
	v_mfma_f32_16x16x32_bf16 v[8:11], v[176:179], v[200:203], v[8:11]
	v_mfma_f32_16x16x32_bf16 v[4:7], v[168:171], v[208:211], v[4:7]
	v_mfma_f32_16x16x32_bf16 v[0:3], v[176:179], v[208:211], v[0:3]
	s_setprio 0
	s_barrier
	s_add_i32 s27, 0, 0x18000
	s_add_i32 s28, 0, 0x1c000
	v_add_u32_e32 v100, s27, v249
	v_add_u32_e32 v154, s28, v249
	ds_read_b128 v[88:91], v100
	ds_read_b128 v[92:95], v100 offset:1024
	ds_read_b128 v[96:99], v100 offset:2048
	ds_read_b128 v[100:103], v100 offset:3072
	ds_read_b128 v[164:167], v154
	ds_read_b128 v[168:171], v154 offset:1024
	ds_read_b128 v[172:175], v154 offset:2048
	ds_read_b128 v[176:179], v154 offset:3072
	s_add_u32 s20, s20, 0x100000
	s_addc_u32 s21, s21, 0
	s_mov_b32 m0, s74
	ds_read_b128 v[180:183], v251 offset:32768
	ds_read_b128 v[184:187], v251 offset:33792
	ds_read_b128 v[188:191], v251 offset:34816
	ds_read_b128 v[192:195], v251 offset:35840
	ds_read_b128 v[196:199], v251 offset:36864
	ds_read_b128 v[200:203], v251 offset:37888
	ds_read_b128 v[204:207], v251 offset:38912
	ds_read_b128 v[208:211], v251 offset:39936
	global_load_lds_dwordx4 v144, s[20:21]
	s_mov_b32 m0, s75
	s_nop 0
	global_load_lds_dwordx4 v146, s[20:21]
	s_waitcnt vmcnt(8)
	s_waitcnt lgkmcnt(0)
	s_barrier
	s_setprio 1
	s_waitcnt lgkmcnt(0)
	v_mfma_f32_16x16x32_bf16 v[140:143], v[88:91], v[180:183], v[140:143]
	v_mfma_f32_16x16x32_bf16 v[136:139], v[96:99], v[180:183], v[136:139]
	v_mfma_f32_16x16x32_bf16 v[132:135], v[88:91], v[188:191], v[132:135]
	v_mfma_f32_16x16x32_bf16 v[128:131], v[96:99], v[188:191], v[128:131]
	v_mfma_f32_16x16x32_bf16 v[124:127], v[88:91], v[196:199], v[124:127]
	v_mfma_f32_16x16x32_bf16 v[120:123], v[96:99], v[196:199], v[120:123]
	v_mfma_f32_16x16x32_bf16 v[116:119], v[88:91], v[204:207], v[116:119]
	v_mfma_f32_16x16x32_bf16 v[112:115], v[96:99], v[204:207], v[112:115]
	v_mfma_f32_16x16x32_bf16 v[140:143], v[92:95], v[184:187], v[140:143]
	v_mfma_f32_16x16x32_bf16 v[136:139], v[100:103], v[184:187], v[136:139]
	v_mfma_f32_16x16x32_bf16 v[132:135], v[92:95], v[192:195], v[132:135]
	v_mfma_f32_16x16x32_bf16 v[128:131], v[100:103], v[192:195], v[128:131]
	v_mfma_f32_16x16x32_bf16 v[124:127], v[92:95], v[200:203], v[124:127]
	v_mfma_f32_16x16x32_bf16 v[120:123], v[100:103], v[200:203], v[120:123]
	v_mfma_f32_16x16x32_bf16 v[116:119], v[92:95], v[208:211], v[116:119]
	v_mfma_f32_16x16x32_bf16 v[112:115], v[100:103], v[208:211], v[112:115]
	s_setprio 0
	s_setprio 1
	v_mfma_f32_16x16x32_bf16 v[60:63], v[164:167], v[180:183], v[60:63]
	v_mfma_f32_16x16x32_bf16 v[56:59], v[172:175], v[180:183], v[56:59]
	v_mfma_f32_16x16x32_bf16 v[52:55], v[164:167], v[188:191], v[52:55]
	v_mfma_f32_16x16x32_bf16 v[48:51], v[172:175], v[188:191], v[48:51]
	v_mfma_f32_16x16x32_bf16 v[44:47], v[164:167], v[196:199], v[44:47]
	v_mfma_f32_16x16x32_bf16 v[40:43], v[172:175], v[196:199], v[40:43]
	v_mfma_f32_16x16x32_bf16 v[36:39], v[164:167], v[204:207], v[36:39]
	v_mfma_f32_16x16x32_bf16 v[32:35], v[172:175], v[204:207], v[32:35]
	v_mfma_f32_16x16x32_bf16 v[60:63], v[168:171], v[184:187], v[60:63]
	v_mfma_f32_16x16x32_bf16 v[56:59], v[176:179], v[184:187], v[56:59]
	v_mfma_f32_16x16x32_bf16 v[52:55], v[168:171], v[192:195], v[52:55]
	v_mfma_f32_16x16x32_bf16 v[48:51], v[176:179], v[192:195], v[48:51]
	v_mfma_f32_16x16x32_bf16 v[44:47], v[168:171], v[200:203], v[44:47]
	v_mfma_f32_16x16x32_bf16 v[40:43], v[176:179], v[200:203], v[40:43]
	v_mfma_f32_16x16x32_bf16 v[36:39], v[168:171], v[208:211], v[36:39]
	v_mfma_f32_16x16x32_bf16 v[32:35], v[176:179], v[208:211], v[32:35]
	s_setprio 0
	s_barrier
	s_add_i32 s20, s27, s62
	v_lshl_add_u64 v[212:213], v[212:213], 0, s[70:71]
	s_mov_b32 m0, s20
	ds_read_b128 v[180:183], v251 offset:49152
	ds_read_b128 v[184:187], v251 offset:50176
	ds_read_b128 v[188:191], v251 offset:51200
	ds_read_b128 v[192:195], v251 offset:52224
	ds_read_b128 v[196:199], v251 offset:53248
	ds_read_b128 v[200:203], v251 offset:54272
	ds_read_b128 v[204:207], v251 offset:55296
	ds_read_b128 v[208:211], v251 offset:56320
	global_load_lds_dwordx4 v[212:213], off
	s_add_i32 m0, s20, 0x2000
	s_add_u32 s12, s12, 0x100080
	v_lshl_add_u64 v[212:213], v[214:215], 0, s[70:71]
	s_addc_u32 s13, s13, 0
	s_add_i32 s20, s28, s62
	global_load_lds_dwordx4 v[212:213], off
	s_mov_b32 m0, s20
	s_nop 0
	global_load_lds_dwordx4 v152, s[12:13]
	s_add_i32 m0, s20, 0x2000
	s_nop 0
	global_load_lds_dwordx4 v148, s[12:13]
	v_lshl_add_u64 v[212:213], v[216:217], 0, s[70:71]
	s_mov_b32 m0, s69
	s_nop 0
	global_load_lds_dwordx4 v[212:213], off
	v_lshl_add_u64 v[212:213], v[218:219], 0, s[70:71]
	s_mov_b32 m0, s92
	s_nop 0
	global_load_lds_dwordx4 v[212:213], off
	s_waitcnt vmcnt(8)
	s_waitcnt lgkmcnt(0)
	s_barrier
	s_setprio 1
	s_waitcnt lgkmcnt(0)
	v_mfma_f32_16x16x32_bf16 v[108:111], v[88:91], v[180:183], v[108:111]
	v_mfma_f32_16x16x32_bf16 v[104:107], v[96:99], v[180:183], v[104:107]
	v_mfma_f32_16x16x32_bf16 v[84:87], v[88:91], v[188:191], v[84:87]
	v_mfma_f32_16x16x32_bf16 v[80:83], v[96:99], v[188:191], v[80:83]
	v_mfma_f32_16x16x32_bf16 v[76:79], v[88:91], v[196:199], v[76:79]
	v_mfma_f32_16x16x32_bf16 v[72:75], v[96:99], v[196:199], v[72:75]
	v_mfma_f32_16x16x32_bf16 v[68:71], v[88:91], v[204:207], v[68:71]
	v_mfma_f32_16x16x32_bf16 v[64:67], v[96:99], v[204:207], v[64:67]
	v_mfma_f32_16x16x32_bf16 v[108:111], v[92:95], v[184:187], v[108:111]
	v_mfma_f32_16x16x32_bf16 v[104:107], v[100:103], v[184:187], v[104:107]
	v_mfma_f32_16x16x32_bf16 v[84:87], v[92:95], v[192:195], v[84:87]
	v_mfma_f32_16x16x32_bf16 v[80:83], v[100:103], v[192:195], v[80:83]
	v_mfma_f32_16x16x32_bf16 v[76:79], v[92:95], v[200:203], v[76:79]
	v_mfma_f32_16x16x32_bf16 v[72:75], v[100:103], v[200:203], v[72:75]
	v_mfma_f32_16x16x32_bf16 v[68:71], v[92:95], v[208:211], v[68:71]
	v_mfma_f32_16x16x32_bf16 v[64:67], v[100:103], v[208:211], v[64:67]
	s_setprio 0
	s_setprio 1
	v_mfma_f32_16x16x32_bf16 v[28:31], v[164:167], v[180:183], v[28:31]
	v_mfma_f32_16x16x32_bf16 v[24:27], v[172:175], v[180:183], v[24:27]
	v_mfma_f32_16x16x32_bf16 v[20:23], v[164:167], v[188:191], v[20:23]
	v_mfma_f32_16x16x32_bf16 v[16:19], v[172:175], v[188:191], v[16:19]
	v_mfma_f32_16x16x32_bf16 v[12:15], v[164:167], v[196:199], v[12:15]
	v_mfma_f32_16x16x32_bf16 v[8:11], v[172:175], v[196:199], v[8:11]
	v_mfma_f32_16x16x32_bf16 v[4:7], v[164:167], v[204:207], v[4:7]
	v_mfma_f32_16x16x32_bf16 v[0:3], v[172:175], v[204:207], v[0:3]
	v_mfma_f32_16x16x32_bf16 v[28:31], v[168:171], v[184:187], v[28:31]
	v_mfma_f32_16x16x32_bf16 v[24:27], v[176:179], v[184:187], v[24:27]
	v_mfma_f32_16x16x32_bf16 v[20:23], v[168:171], v[192:195], v[20:23]
	v_mfma_f32_16x16x32_bf16 v[16:19], v[176:179], v[192:195], v[16:19]
	v_mfma_f32_16x16x32_bf16 v[12:15], v[168:171], v[200:203], v[12:15]
	v_mfma_f32_16x16x32_bf16 v[8:11], v[176:179], v[200:203], v[8:11]
	v_mfma_f32_16x16x32_bf16 v[4:7], v[168:171], v[208:211], v[4:7]
	v_mfma_f32_16x16x32_bf16 v[0:3], v[176:179], v[208:211], v[0:3]
	s_setprio 0
	s_barrier
	s_add_i32 s26, s26, 2
	s_add_u32 s10, s10, 0x100
	s_addc_u32 s11, s11, 0
	s_add_u32 s24, s24, 0x100
	s_addc_u32 s25, s25, 0
	s_cmp_gt_u32 s26, 61
	s_cbranch_scc0 .LBB0_635
	s_and_b64 vcc, exec, s[0:1]
	s_cbranch_vccz .LBB0_638
	s_barrier

.LBB0_790:
	s_add_u32 s30, s28, 0xfffc0080
	s_addc_u32 s31, s29, -1
	s_add_i32 s82, 0, 0x10000
	s_cmp_eq_u32 s77, 12
	s_cselect_b32 s69, s63, s31
	s_cselect_b32 s68, s73, s30
	s_cselect_b32 s31, s45, s76
	s_cselect_b32 s30, s74, s75
	s_add_i32 s84, 0, 0x14000
	v_add_u32_e32 v118, s82, v167
	v_add_u32_e32 v164, s84, v167
	ds_read_b128 v[102:105], v118
	ds_read_b128 v[110:113], v118 offset:1024
	ds_read_b128 v[114:117], v118 offset:2048
	ds_read_b128 v[118:121], v118 offset:3072
	ds_read_b128 v[160:163], v164
	ds_read_b128 v[172:175], v164 offset:1024
	ds_read_b128 v[176:179], v164 offset:2048
	ds_read_b128 v[180:183], v164 offset:3072
	s_add_i32 m0, s11, 0xc000
	ds_read_b128 v[190:193], v171
	ds_read_b128 v[194:197], v171 offset:1024
	ds_read_b128 v[198:201], v171 offset:2048
	ds_read_b128 v[202:205], v171 offset:3072
	ds_read_b128 v[206:209], v171 offset:4096
	ds_read_b128 v[210:213], v171 offset:5120
	ds_read_b128 v[214:217], v171 offset:6144
	ds_read_b128 v[218:221], v171 offset:7168
	global_load_lds_dwordx4 v156, s[28:29]
	s_add_i32 m0, s11, 0xe000
	s_nop 0
	global_load_lds_dwordx4 v158, s[28:29]
	s_waitcnt vmcnt(8)
	s_waitcnt lgkmcnt(0)
	s_barrier
	s_setprio 1
	s_waitcnt lgkmcnt(0)
	v_mfma_f32_16x16x32_bf16 v[142:145], v[102:105], v[190:193], v[142:145]
	v_mfma_f32_16x16x32_bf16 v[138:141], v[114:117], v[190:193], v[138:141]
	v_mfma_f32_16x16x32_bf16 v[126:129], v[102:105], v[198:201], v[126:129]
	v_mfma_f32_16x16x32_bf16 v[122:125], v[114:117], v[198:201], v[122:125]
	v_mfma_f32_16x16x32_bf16 v[94:97], v[102:105], v[206:209], v[94:97]
	v_mfma_f32_16x16x32_bf16 v[90:93], v[114:117], v[206:209], v[90:93]
	v_mfma_f32_16x16x32_bf16 v[78:81], v[102:105], v[214:217], v[78:81]
	v_mfma_f32_16x16x32_bf16 v[74:77], v[114:117], v[214:217], v[74:77]
	v_mfma_f32_16x16x32_bf16 v[142:145], v[110:113], v[194:197], v[142:145]
	v_mfma_f32_16x16x32_bf16 v[138:141], v[118:121], v[194:197], v[138:141]
	v_mfma_f32_16x16x32_bf16 v[126:129], v[110:113], v[202:205], v[126:129]
	v_mfma_f32_16x16x32_bf16 v[122:125], v[118:121], v[202:205], v[122:125]
	v_mfma_f32_16x16x32_bf16 v[94:97], v[110:113], v[210:213], v[94:97]
	v_mfma_f32_16x16x32_bf16 v[90:93], v[118:121], v[210:213], v[90:93]
	v_mfma_f32_16x16x32_bf16 v[78:81], v[110:113], v[218:221], v[78:81]
	v_mfma_f32_16x16x32_bf16 v[74:77], v[118:121], v[218:221], v[74:77]
	s_setprio 0
	s_setprio 1
	v_mfma_f32_16x16x32_bf16 v[134:137], v[160:163], v[190:193], v[134:137]
	v_mfma_f32_16x16x32_bf16 v[130:133], v[176:179], v[190:193], v[130:133]
	v_mfma_f32_16x16x32_bf16 v[106:109], v[160:163], v[198:201], v[106:109]
	v_mfma_f32_16x16x32_bf16 v[98:101], v[176:179], v[198:201], v[98:101]
	v_mfma_f32_16x16x32_bf16 v[86:89], v[160:163], v[206:209], v[86:89]
	v_mfma_f32_16x16x32_bf16 v[82:85], v[176:179], v[206:209], v[82:85]
	v_mfma_f32_16x16x32_bf16 v[70:73], v[160:163], v[214:217], v[70:73]
	v_mfma_f32_16x16x32_bf16 v[66:69], v[176:179], v[214:217], v[66:69]
	v_mfma_f32_16x16x32_bf16 v[134:137], v[172:175], v[194:197], v[134:137]
	v_mfma_f32_16x16x32_bf16 v[130:133], v[180:183], v[194:197], v[130:133]
	v_mfma_f32_16x16x32_bf16 v[106:109], v[172:175], v[202:205], v[106:109]
	v_mfma_f32_16x16x32_bf16 v[98:101], v[180:183], v[202:205], v[98:101]
	v_mfma_f32_16x16x32_bf16 v[86:89], v[172:175], v[210:213], v[86:89]
	v_mfma_f32_16x16x32_bf16 v[82:85], v[180:183], v[210:213], v[82:85]
	v_mfma_f32_16x16x32_bf16 v[70:73], v[172:175], v[218:221], v[70:73]
	v_mfma_f32_16x16x32_bf16 v[66:69], v[180:183], v[218:221], v[66:69]
	s_setprio 0
	s_barrier
	s_add_i32 s82, s82, s10
	v_lshl_add_u64 v[164:165], s[30:31], 0, v[148:149]
	s_mov_b32 m0, s82
	ds_read_b128 v[190:193], v171 offset:16384
	ds_read_b128 v[194:197], v171 offset:17408
	ds_read_b128 v[198:201], v171 offset:18432
	ds_read_b128 v[202:205], v171 offset:19456
	ds_read_b128 v[206:209], v171 offset:20480
	ds_read_b128 v[210:213], v171 offset:21504
	ds_read_b128 v[214:217], v171 offset:22528
	ds_read_b128 v[218:221], v171 offset:23552
	global_load_lds_dwordx4 v148, s[30:31]
	s_add_i32 m0, s82, 0x2000
	s_add_u32 s82, s30, 0x40000
	v_lshl_add_u64 v[168:169], s[30:31], 0, v[152:153]
	s_addc_u32 s83, s31, 0
	s_add_i32 s84, s84, s10
	global_load_lds_dwordx4 v152, s[30:31]
	s_mov_b32 m0, s84
	v_lshl_add_u64 v[222:223], s[68:69], 0, v[150:151]
	global_load_lds_dwordx4 v148, s[82:83]
	s_add_i32 m0, s84, 0x2000
	s_nop 0
	global_load_lds_dwordx4 v152, s[82:83]
	v_lshl_add_u64 v[184:185], s[68:69], 0, v[146:147]
	s_mov_b32 m0, s11
	s_nop 0
	global_load_lds_dwordx4 v146, s[68:69]
	s_mov_b32 m0, s13
	s_nop 0
	global_load_lds_dwordx4 v150, s[68:69]
	s_waitcnt vmcnt(8)
	s_waitcnt lgkmcnt(0)
	s_barrier
	s_setprio 1
	s_waitcnt lgkmcnt(0)
	v_mfma_f32_16x16x32_bf16 v[60:63], v[102:105], v[190:193], v[60:63]
	v_mfma_f32_16x16x32_bf16 v[56:59], v[114:117], v[190:193], v[56:59]
	v_mfma_f32_16x16x32_bf16 v[44:47], v[102:105], v[198:201], v[44:47]
	v_mfma_f32_16x16x32_bf16 v[40:43], v[114:117], v[198:201], v[40:43]
	v_mfma_f32_16x16x32_bf16 v[28:31], v[102:105], v[206:209], v[28:31]
	v_mfma_f32_16x16x32_bf16 v[24:27], v[114:117], v[206:209], v[24:27]
	v_mfma_f32_16x16x32_bf16 v[12:15], v[102:105], v[214:217], v[12:15]
	v_mfma_f32_16x16x32_bf16 v[8:11], v[114:117], v[214:217], v[8:11]
	v_mfma_f32_16x16x32_bf16 v[60:63], v[110:113], v[194:197], v[60:63]
	v_mfma_f32_16x16x32_bf16 v[56:59], v[118:121], v[194:197], v[56:59]
	v_mfma_f32_16x16x32_bf16 v[44:47], v[110:113], v[202:205], v[44:47]
	v_mfma_f32_16x16x32_bf16 v[40:43], v[118:121], v[202:205], v[40:43]
	v_mfma_f32_16x16x32_bf16 v[28:31], v[110:113], v[210:213], v[28:31]
	v_mfma_f32_16x16x32_bf16 v[24:27], v[118:121], v[210:213], v[24:27]
	v_mfma_f32_16x16x32_bf16 v[12:15], v[110:113], v[218:221], v[12:15]
	v_mfma_f32_16x16x32_bf16 v[8:11], v[118:121], v[218:221], v[8:11]
	s_setprio 0
	s_setprio 1
	v_mfma_f32_16x16x32_bf16 v[52:55], v[160:163], v[190:193], v[52:55]
	v_mfma_f32_16x16x32_bf16 v[48:51], v[176:179], v[190:193], v[48:51]
	v_mfma_f32_16x16x32_bf16 v[36:39], v[160:163], v[198:201], v[36:39]
	v_mfma_f32_16x16x32_bf16 v[32:35], v[176:179], v[198:201], v[32:35]
	v_mfma_f32_16x16x32_bf16 v[20:23], v[160:163], v[206:209], v[20:23]
	v_mfma_f32_16x16x32_bf16 v[16:19], v[176:179], v[206:209], v[16:19]
	v_mfma_f32_16x16x32_bf16 v[4:7], v[160:163], v[214:217], v[4:7]
	v_mfma_f32_16x16x32_bf16 v[0:3], v[176:179], v[214:217], v[0:3]
	v_mfma_f32_16x16x32_bf16 v[52:55], v[172:175], v[194:197], v[52:55]
	v_mfma_f32_16x16x32_bf16 v[48:51], v[180:183], v[194:197], v[48:51]
	v_mfma_f32_16x16x32_bf16 v[36:39], v[172:175], v[202:205], v[36:39]
	v_mfma_f32_16x16x32_bf16 v[32:35], v[180:183], v[202:205], v[32:35]
	v_mfma_f32_16x16x32_bf16 v[20:23], v[172:175], v[210:213], v[20:23]
	v_mfma_f32_16x16x32_bf16 v[16:19], v[180:183], v[210:213], v[16:19]
	v_mfma_f32_16x16x32_bf16 v[4:7], v[172:175], v[218:221], v[4:7]
	v_mfma_f32_16x16x32_bf16 v[0:3], v[180:183], v[218:221], v[0:3]
	s_setprio 0
	s_barrier
	s_add_i32 s82, 0, 0x18000
	s_add_i32 s83, 0, 0x1c000
	v_add_u32_e32 v118, s82, v167
	v_add_u32_e32 v166, s83, v167
	ds_read_b128 v[102:105], v118
	ds_read_b128 v[110:113], v118 offset:1024
	ds_read_b128 v[114:117], v118 offset:2048
	ds_read_b128 v[118:121], v118 offset:3072
	ds_read_b128 v[160:163], v166
	ds_read_b128 v[172:175], v166 offset:1024
	ds_read_b128 v[176:179], v166 offset:2048
	ds_read_b128 v[180:183], v166 offset:3072
	s_add_u32 s68, s68, 0x40000
	s_addc_u32 s69, s69, 0
	s_mov_b32 m0, s19
	ds_read_b128 v[190:193], v171 offset:32768
	ds_read_b128 v[194:197], v171 offset:33792
	ds_read_b128 v[198:201], v171 offset:34816
	ds_read_b128 v[202:205], v171 offset:35840
	ds_read_b128 v[206:209], v171 offset:36864
	ds_read_b128 v[210:213], v171 offset:37888
	ds_read_b128 v[214:217], v171 offset:38912
	ds_read_b128 v[218:221], v171 offset:39936
	global_load_lds_dwordx4 v146, s[68:69]
	s_mov_b32 m0, s34
	s_nop 0
	global_load_lds_dwordx4 v150, s[68:69]
	s_waitcnt vmcnt(8)
	s_waitcnt lgkmcnt(0)
	s_barrier
	s_setprio 1
	s_waitcnt lgkmcnt(0)
	v_mfma_f32_16x16x32_bf16 v[142:145], v[102:105], v[190:193], v[142:145]
	v_mfma_f32_16x16x32_bf16 v[138:141], v[114:117], v[190:193], v[138:141]
	v_mfma_f32_16x16x32_bf16 v[126:129], v[102:105], v[198:201], v[126:129]
	v_mfma_f32_16x16x32_bf16 v[122:125], v[114:117], v[198:201], v[122:125]
	v_mfma_f32_16x16x32_bf16 v[94:97], v[102:105], v[206:209], v[94:97]
	v_mfma_f32_16x16x32_bf16 v[90:93], v[114:117], v[206:209], v[90:93]
	v_mfma_f32_16x16x32_bf16 v[78:81], v[102:105], v[214:217], v[78:81]
	v_mfma_f32_16x16x32_bf16 v[74:77], v[114:117], v[214:217], v[74:77]
	v_mfma_f32_16x16x32_bf16 v[142:145], v[110:113], v[194:197], v[142:145]
	v_mfma_f32_16x16x32_bf16 v[138:141], v[118:121], v[194:197], v[138:141]
	v_mfma_f32_16x16x32_bf16 v[126:129], v[110:113], v[202:205], v[126:129]
	v_mfma_f32_16x16x32_bf16 v[122:125], v[118:121], v[202:205], v[122:125]
	v_mfma_f32_16x16x32_bf16 v[94:97], v[110:113], v[210:213], v[94:97]
	v_mfma_f32_16x16x32_bf16 v[90:93], v[118:121], v[210:213], v[90:93]
	v_mfma_f32_16x16x32_bf16 v[78:81], v[110:113], v[218:221], v[78:81]
	v_mfma_f32_16x16x32_bf16 v[74:77], v[118:121], v[218:221], v[74:77]
	s_setprio 0
	s_setprio 1
	v_mfma_f32_16x16x32_bf16 v[134:137], v[160:163], v[190:193], v[134:137]
	v_mfma_f32_16x16x32_bf16 v[130:133], v[176:179], v[190:193], v[130:133]
	v_mfma_f32_16x16x32_bf16 v[106:109], v[160:163], v[198:201], v[106:109]
	v_mfma_f32_16x16x32_bf16 v[98:101], v[176:179], v[198:201], v[98:101]
	v_mfma_f32_16x16x32_bf16 v[86:89], v[160:163], v[206:209], v[86:89]
	v_mfma_f32_16x16x32_bf16 v[82:85], v[176:179], v[206:209], v[82:85]
	v_mfma_f32_16x16x32_bf16 v[70:73], v[160:163], v[214:217], v[70:73]
	v_mfma_f32_16x16x32_bf16 v[66:69], v[176:179], v[214:217], v[66:69]
	v_mfma_f32_16x16x32_bf16 v[134:137], v[172:175], v[194:197], v[134:137]
	v_mfma_f32_16x16x32_bf16 v[130:133], v[180:183], v[194:197], v[130:133]
	v_mfma_f32_16x16x32_bf16 v[106:109], v[172:175], v[202:205], v[106:109]
	v_mfma_f32_16x16x32_bf16 v[98:101], v[180:183], v[202:205], v[98:101]
	v_mfma_f32_16x16x32_bf16 v[86:89], v[172:175], v[210:213], v[86:89]
	v_mfma_f32_16x16x32_bf16 v[82:85], v[180:183], v[210:213], v[82:85]
	v_mfma_f32_16x16x32_bf16 v[70:73], v[172:175], v[218:221], v[70:73]
	v_mfma_f32_16x16x32_bf16 v[66:69], v[180:183], v[218:221], v[66:69]
	s_setprio 0
	s_barrier
	s_add_i32 s68, s82, s10
	v_lshl_add_u64 v[164:165], v[164:165], 0, s[16:17]
	s_mov_b32 m0, s68
	ds_read_b128 v[190:193], v171 offset:49152
	ds_read_b128 v[194:197], v171 offset:50176
	ds_read_b128 v[198:201], v171 offset:51200
	ds_read_b128 v[202:205], v171 offset:52224
	ds_read_b128 v[206:209], v171 offset:53248
	ds_read_b128 v[210:213], v171 offset:54272
	ds_read_b128 v[214:217], v171 offset:55296
	ds_read_b128 v[218:221], v171 offset:56320
	global_load_lds_dwordx4 v[164:165], off
	s_add_i32 m0, s68, 0x2000
	s_add_u32 s30, s30, 0x40080
	v_lshl_add_u64 v[164:165], v[168:169], 0, s[16:17]
	s_addc_u32 s31, s31, 0
	s_add_i32 s68, s83, s10
	global_load_lds_dwordx4 v[164:165], off
	s_mov_b32 m0, s68
	s_nop 0
	global_load_lds_dwordx4 v148, s[30:31]
	s_add_i32 m0, s68, 0x2000
	s_nop 0
	global_load_lds_dwordx4 v152, s[30:31]
	v_lshl_add_u64 v[164:165], v[184:185], 0, s[16:17]
	s_mov_b32 m0, s46
	s_nop 0
	global_load_lds_dwordx4 v[164:165], off
	v_lshl_add_u64 v[164:165], v[222:223], 0, s[16:17]
	s_mov_b32 m0, s47
	s_nop 0
	global_load_lds_dwordx4 v[164:165], off
	s_waitcnt vmcnt(8)
	s_waitcnt lgkmcnt(0)
	s_barrier
	s_setprio 1
	s_waitcnt lgkmcnt(0)
	v_mfma_f32_16x16x32_bf16 v[60:63], v[102:105], v[190:193], v[60:63]
	v_mfma_f32_16x16x32_bf16 v[56:59], v[114:117], v[190:193], v[56:59]
	v_mfma_f32_16x16x32_bf16 v[44:47], v[102:105], v[198:201], v[44:47]
	v_mfma_f32_16x16x32_bf16 v[40:43], v[114:117], v[198:201], v[40:43]
	v_mfma_f32_16x16x32_bf16 v[28:31], v[102:105], v[206:209], v[28:31]
	v_mfma_f32_16x16x32_bf16 v[24:27], v[114:117], v[206:209], v[24:27]
	v_mfma_f32_16x16x32_bf16 v[12:15], v[102:105], v[214:217], v[12:15]
	v_mfma_f32_16x16x32_bf16 v[8:11], v[114:117], v[214:217], v[8:11]
	v_mfma_f32_16x16x32_bf16 v[60:63], v[110:113], v[194:197], v[60:63]
	v_mfma_f32_16x16x32_bf16 v[56:59], v[118:121], v[194:197], v[56:59]
	v_mfma_f32_16x16x32_bf16 v[44:47], v[110:113], v[202:205], v[44:47]
	v_mfma_f32_16x16x32_bf16 v[40:43], v[118:121], v[202:205], v[40:43]
	v_mfma_f32_16x16x32_bf16 v[28:31], v[110:113], v[210:213], v[28:31]
	v_mfma_f32_16x16x32_bf16 v[24:27], v[118:121], v[210:213], v[24:27]
	v_mfma_f32_16x16x32_bf16 v[12:15], v[110:113], v[218:221], v[12:15]
	v_mfma_f32_16x16x32_bf16 v[8:11], v[118:121], v[218:221], v[8:11]
	s_setprio 0
	s_setprio 1
	v_mfma_f32_16x16x32_bf16 v[52:55], v[160:163], v[190:193], v[52:55]
	v_mfma_f32_16x16x32_bf16 v[48:51], v[176:179], v[190:193], v[48:51]
	v_mfma_f32_16x16x32_bf16 v[36:39], v[160:163], v[198:201], v[36:39]
	v_mfma_f32_16x16x32_bf16 v[32:35], v[176:179], v[198:201], v[32:35]
	v_mfma_f32_16x16x32_bf16 v[20:23], v[160:163], v[206:209], v[20:23]
	v_mfma_f32_16x16x32_bf16 v[16:19], v[176:179], v[206:209], v[16:19]
	v_mfma_f32_16x16x32_bf16 v[4:7], v[160:163], v[214:217], v[4:7]
	v_mfma_f32_16x16x32_bf16 v[0:3], v[176:179], v[214:217], v[0:3]
	v_mfma_f32_16x16x32_bf16 v[52:55], v[172:175], v[194:197], v[52:55]
	v_mfma_f32_16x16x32_bf16 v[48:51], v[180:183], v[194:197], v[48:51]
	v_mfma_f32_16x16x32_bf16 v[36:39], v[172:175], v[202:205], v[36:39]
	v_mfma_f32_16x16x32_bf16 v[32:35], v[180:183], v[202:205], v[32:35]
	v_mfma_f32_16x16x32_bf16 v[20:23], v[172:175], v[210:213], v[20:23]
	v_mfma_f32_16x16x32_bf16 v[16:19], v[180:183], v[210:213], v[16:19]
	v_mfma_f32_16x16x32_bf16 v[4:7], v[172:175], v[218:221], v[4:7]
	v_mfma_f32_16x16x32_bf16 v[0:3], v[180:183], v[218:221], v[0:3]
	s_setprio 0
	s_barrier
	s_add_i32 s77, s77, 2
	s_add_u32 s28, s28, 0x100
	s_addc_u32 s29, s29, 0
	s_add_u32 s75, s75, 0x100
	s_addc_u32 s76, s76, 0
	s_cmp_gt_u32 s77, 13
	s_cbranch_scc0 .LBB0_790
	s_and_b64 vcc, exec, s[42:43]
	s_cbranch_vccz .LBB0_793
	s_barrier

.LBB0_893:
	s_add_u32 s30, s28, 0xfffc0080
	s_addc_u32 s31, s29, -1
	s_add_i32 s84, 0, 0x10000
	s_cmp_eq_u32 s83, 12
	s_cselect_b32 s69, s63, s31
	s_cselect_b32 s68, s75, s30
	s_cselect_b32 s31, s45, s82
	s_cselect_b32 s30, s76, s77
	s_add_i32 s85, 0, 0x14000
	v_add_u32_e32 v110, s84, v167
	v_add_u32_e32 v164, s85, v167
	ds_read_b128 v[98:101], v110
	ds_read_b128 v[102:105], v110 offset:1024
	ds_read_b128 v[106:109], v110 offset:2048
	ds_read_b128 v[110:113], v110 offset:3072
	ds_read_b128 v[160:163], v164
	ds_read_b128 v[172:175], v164 offset:1024
	ds_read_b128 v[176:179], v164 offset:2048
	ds_read_b128 v[180:183], v164 offset:3072
	s_add_i32 m0, s11, 0xc000
	ds_read_b128 v[190:193], v171
	ds_read_b128 v[194:197], v171 offset:1024
	ds_read_b128 v[198:201], v171 offset:2048
	ds_read_b128 v[202:205], v171 offset:3072
	ds_read_b128 v[206:209], v171 offset:4096
	ds_read_b128 v[210:213], v171 offset:5120
	ds_read_b128 v[214:217], v171 offset:6144
	ds_read_b128 v[218:221], v171 offset:7168
	global_load_lds_dwordx4 v156, s[28:29]
	s_add_i32 m0, s11, 0xe000
	s_nop 0
	global_load_lds_dwordx4 v158, s[28:29]
	s_waitcnt vmcnt(8)
	s_waitcnt lgkmcnt(0)
	s_barrier
	s_setprio 1
	s_waitcnt lgkmcnt(0)
	v_mfma_f32_16x16x32_bf16 v[142:145], v[98:101], v[190:193], v[142:145]
	v_mfma_f32_16x16x32_bf16 v[138:141], v[106:109], v[190:193], v[138:141]
	v_mfma_f32_16x16x32_bf16 v[126:129], v[98:101], v[198:201], v[126:129]
	v_mfma_f32_16x16x32_bf16 v[122:125], v[106:109], v[198:201], v[122:125]
	v_mfma_f32_16x16x32_bf16 v[94:97], v[98:101], v[206:209], v[94:97]
	v_mfma_f32_16x16x32_bf16 v[90:93], v[106:109], v[206:209], v[90:93]
	v_mfma_f32_16x16x32_bf16 v[78:81], v[98:101], v[214:217], v[78:81]
	v_mfma_f32_16x16x32_bf16 v[74:77], v[106:109], v[214:217], v[74:77]
	v_mfma_f32_16x16x32_bf16 v[142:145], v[102:105], v[194:197], v[142:145]
	v_mfma_f32_16x16x32_bf16 v[138:141], v[110:113], v[194:197], v[138:141]
	v_mfma_f32_16x16x32_bf16 v[126:129], v[102:105], v[202:205], v[126:129]
	v_mfma_f32_16x16x32_bf16 v[122:125], v[110:113], v[202:205], v[122:125]
	v_mfma_f32_16x16x32_bf16 v[94:97], v[102:105], v[210:213], v[94:97]
	v_mfma_f32_16x16x32_bf16 v[90:93], v[110:113], v[210:213], v[90:93]
	v_mfma_f32_16x16x32_bf16 v[78:81], v[102:105], v[218:221], v[78:81]
	v_mfma_f32_16x16x32_bf16 v[74:77], v[110:113], v[218:221], v[74:77]
	s_setprio 0
	s_setprio 1
	v_mfma_f32_16x16x32_bf16 v[134:137], v[160:163], v[190:193], v[134:137]
	v_mfma_f32_16x16x32_bf16 v[130:133], v[176:179], v[190:193], v[130:133]
	v_mfma_f32_16x16x32_bf16 v[118:121], v[160:163], v[198:201], v[118:121]
	v_mfma_f32_16x16x32_bf16 v[114:117], v[176:179], v[198:201], v[114:117]
	v_mfma_f32_16x16x32_bf16 v[86:89], v[160:163], v[206:209], v[86:89]
	v_mfma_f32_16x16x32_bf16 v[82:85], v[176:179], v[206:209], v[82:85]
	v_mfma_f32_16x16x32_bf16 v[70:73], v[160:163], v[214:217], v[70:73]
	v_mfma_f32_16x16x32_bf16 v[66:69], v[176:179], v[214:217], v[66:69]
	v_mfma_f32_16x16x32_bf16 v[134:137], v[172:175], v[194:197], v[134:137]
	v_mfma_f32_16x16x32_bf16 v[130:133], v[180:183], v[194:197], v[130:133]
	v_mfma_f32_16x16x32_bf16 v[118:121], v[172:175], v[202:205], v[118:121]
	v_mfma_f32_16x16x32_bf16 v[114:117], v[180:183], v[202:205], v[114:117]
	v_mfma_f32_16x16x32_bf16 v[86:89], v[172:175], v[210:213], v[86:89]
	v_mfma_f32_16x16x32_bf16 v[82:85], v[180:183], v[210:213], v[82:85]
	v_mfma_f32_16x16x32_bf16 v[70:73], v[172:175], v[218:221], v[70:73]
	v_mfma_f32_16x16x32_bf16 v[66:69], v[180:183], v[218:221], v[66:69]
	s_setprio 0
	s_barrier
	s_add_i32 s84, s84, s10
	v_lshl_add_u64 v[164:165], s[30:31], 0, v[148:149]
	s_mov_b32 m0, s84
	ds_read_b128 v[190:193], v171 offset:16384
	ds_read_b128 v[194:197], v171 offset:17408
	ds_read_b128 v[198:201], v171 offset:18432
	ds_read_b128 v[202:205], v171 offset:19456
	ds_read_b128 v[206:209], v171 offset:20480
	ds_read_b128 v[210:213], v171 offset:21504
	ds_read_b128 v[214:217], v171 offset:22528
	ds_read_b128 v[218:221], v171 offset:23552
	global_load_lds_dwordx4 v148, s[30:31]
	s_add_i32 m0, s84, 0x2000
	s_add_u32 s90, s30, 0x40000
	v_lshl_add_u64 v[168:169], s[30:31], 0, v[152:153]
	s_addc_u32 s91, s31, 0
	s_add_i32 s84, s85, s10
	global_load_lds_dwordx4 v152, s[30:31]
	s_mov_b32 m0, s84
	v_lshl_add_u64 v[222:223], s[68:69], 0, v[150:151]
	global_load_lds_dwordx4 v148, s[90:91]
	s_add_i32 m0, s84, 0x2000
	s_nop 0
	global_load_lds_dwordx4 v152, s[90:91]
	v_lshl_add_u64 v[184:185], s[68:69], 0, v[146:147]
	s_mov_b32 m0, s11
	s_nop 0
	global_load_lds_dwordx4 v146, s[68:69]
	s_mov_b32 m0, s13
	s_nop 0
	global_load_lds_dwordx4 v150, s[68:69]
	s_waitcnt vmcnt(8)
	s_waitcnt lgkmcnt(0)
	s_barrier
	s_setprio 1
	s_waitcnt lgkmcnt(0)
	v_mfma_f32_16x16x32_bf16 v[60:63], v[98:101], v[190:193], v[60:63]
	v_mfma_f32_16x16x32_bf16 v[56:59], v[106:109], v[190:193], v[56:59]
	v_mfma_f32_16x16x32_bf16 v[44:47], v[98:101], v[198:201], v[44:47]
	v_mfma_f32_16x16x32_bf16 v[40:43], v[106:109], v[198:201], v[40:43]
	v_mfma_f32_16x16x32_bf16 v[28:31], v[98:101], v[206:209], v[28:31]
	v_mfma_f32_16x16x32_bf16 v[24:27], v[106:109], v[206:209], v[24:27]
	v_mfma_f32_16x16x32_bf16 v[12:15], v[98:101], v[214:217], v[12:15]
	v_mfma_f32_16x16x32_bf16 v[8:11], v[106:109], v[214:217], v[8:11]
	v_mfma_f32_16x16x32_bf16 v[60:63], v[102:105], v[194:197], v[60:63]
	v_mfma_f32_16x16x32_bf16 v[56:59], v[110:113], v[194:197], v[56:59]
	v_mfma_f32_16x16x32_bf16 v[44:47], v[102:105], v[202:205], v[44:47]
	v_mfma_f32_16x16x32_bf16 v[40:43], v[110:113], v[202:205], v[40:43]
	v_mfma_f32_16x16x32_bf16 v[28:31], v[102:105], v[210:213], v[28:31]
	v_mfma_f32_16x16x32_bf16 v[24:27], v[110:113], v[210:213], v[24:27]
	v_mfma_f32_16x16x32_bf16 v[12:15], v[102:105], v[218:221], v[12:15]
	v_mfma_f32_16x16x32_bf16 v[8:11], v[110:113], v[218:221], v[8:11]
	s_setprio 0
	s_setprio 1
	v_mfma_f32_16x16x32_bf16 v[52:55], v[160:163], v[190:193], v[52:55]
	v_mfma_f32_16x16x32_bf16 v[48:51], v[176:179], v[190:193], v[48:51]
	v_mfma_f32_16x16x32_bf16 v[36:39], v[160:163], v[198:201], v[36:39]
	v_mfma_f32_16x16x32_bf16 v[32:35], v[176:179], v[198:201], v[32:35]
	v_mfma_f32_16x16x32_bf16 v[20:23], v[160:163], v[206:209], v[20:23]
	v_mfma_f32_16x16x32_bf16 v[16:19], v[176:179], v[206:209], v[16:19]
	v_mfma_f32_16x16x32_bf16 v[4:7], v[160:163], v[214:217], v[4:7]
	v_mfma_f32_16x16x32_bf16 v[0:3], v[176:179], v[214:217], v[0:3]
	v_mfma_f32_16x16x32_bf16 v[52:55], v[172:175], v[194:197], v[52:55]
	v_mfma_f32_16x16x32_bf16 v[48:51], v[180:183], v[194:197], v[48:51]
	v_mfma_f32_16x16x32_bf16 v[36:39], v[172:175], v[202:205], v[36:39]
	v_mfma_f32_16x16x32_bf16 v[32:35], v[180:183], v[202:205], v[32:35]
	v_mfma_f32_16x16x32_bf16 v[20:23], v[172:175], v[210:213], v[20:23]
	v_mfma_f32_16x16x32_bf16 v[16:19], v[180:183], v[210:213], v[16:19]
	v_mfma_f32_16x16x32_bf16 v[4:7], v[172:175], v[218:221], v[4:7]
	v_mfma_f32_16x16x32_bf16 v[0:3], v[180:183], v[218:221], v[0:3]
	s_setprio 0
	s_barrier
	s_add_i32 s84, 0, 0x18000
	s_add_i32 s85, 0, 0x1c000
	v_add_u32_e32 v110, s84, v167
	v_add_u32_e32 v166, s85, v167
	ds_read_b128 v[98:101], v110
	ds_read_b128 v[102:105], v110 offset:1024
	ds_read_b128 v[106:109], v110 offset:2048
	ds_read_b128 v[110:113], v110 offset:3072
	ds_read_b128 v[160:163], v166
	ds_read_b128 v[172:175], v166 offset:1024
	ds_read_b128 v[176:179], v166 offset:2048
	ds_read_b128 v[180:183], v166 offset:3072
	s_add_u32 s68, s68, 0x40000
	s_addc_u32 s69, s69, 0
	s_mov_b32 m0, s19
	ds_read_b128 v[190:193], v171 offset:32768
	ds_read_b128 v[194:197], v171 offset:33792
	ds_read_b128 v[198:201], v171 offset:34816
	ds_read_b128 v[202:205], v171 offset:35840
	ds_read_b128 v[206:209], v171 offset:36864
	ds_read_b128 v[210:213], v171 offset:37888
	ds_read_b128 v[214:217], v171 offset:38912
	ds_read_b128 v[218:221], v171 offset:39936
	global_load_lds_dwordx4 v146, s[68:69]
	s_mov_b32 m0, s34
	s_nop 0
	global_load_lds_dwordx4 v150, s[68:69]
	s_waitcnt vmcnt(8)
	s_waitcnt lgkmcnt(0)
	s_barrier
	s_setprio 1
	s_waitcnt lgkmcnt(0)
	v_mfma_f32_16x16x32_bf16 v[142:145], v[98:101], v[190:193], v[142:145]
	v_mfma_f32_16x16x32_bf16 v[138:141], v[106:109], v[190:193], v[138:141]
	v_mfma_f32_16x16x32_bf16 v[126:129], v[98:101], v[198:201], v[126:129]
	v_mfma_f32_16x16x32_bf16 v[122:125], v[106:109], v[198:201], v[122:125]
	v_mfma_f32_16x16x32_bf16 v[94:97], v[98:101], v[206:209], v[94:97]
	v_mfma_f32_16x16x32_bf16 v[90:93], v[106:109], v[206:209], v[90:93]
	v_mfma_f32_16x16x32_bf16 v[78:81], v[98:101], v[214:217], v[78:81]
	v_mfma_f32_16x16x32_bf16 v[74:77], v[106:109], v[214:217], v[74:77]
	v_mfma_f32_16x16x32_bf16 v[142:145], v[102:105], v[194:197], v[142:145]
	v_mfma_f32_16x16x32_bf16 v[138:141], v[110:113], v[194:197], v[138:141]
	v_mfma_f32_16x16x32_bf16 v[126:129], v[102:105], v[202:205], v[126:129]
	v_mfma_f32_16x16x32_bf16 v[122:125], v[110:113], v[202:205], v[122:125]
	v_mfma_f32_16x16x32_bf16 v[94:97], v[102:105], v[210:213], v[94:97]
	v_mfma_f32_16x16x32_bf16 v[90:93], v[110:113], v[210:213], v[90:93]
	v_mfma_f32_16x16x32_bf16 v[78:81], v[102:105], v[218:221], v[78:81]
	v_mfma_f32_16x16x32_bf16 v[74:77], v[110:113], v[218:221], v[74:77]
	s_setprio 0
	s_setprio 1
	v_mfma_f32_16x16x32_bf16 v[134:137], v[160:163], v[190:193], v[134:137]
	v_mfma_f32_16x16x32_bf16 v[130:133], v[176:179], v[190:193], v[130:133]
	v_mfma_f32_16x16x32_bf16 v[118:121], v[160:163], v[198:201], v[118:121]
	v_mfma_f32_16x16x32_bf16 v[114:117], v[176:179], v[198:201], v[114:117]
	v_mfma_f32_16x16x32_bf16 v[86:89], v[160:163], v[206:209], v[86:89]
	v_mfma_f32_16x16x32_bf16 v[82:85], v[176:179], v[206:209], v[82:85]
	v_mfma_f32_16x16x32_bf16 v[70:73], v[160:163], v[214:217], v[70:73]
	v_mfma_f32_16x16x32_bf16 v[66:69], v[176:179], v[214:217], v[66:69]
	v_mfma_f32_16x16x32_bf16 v[134:137], v[172:175], v[194:197], v[134:137]
	v_mfma_f32_16x16x32_bf16 v[130:133], v[180:183], v[194:197], v[130:133]
	v_mfma_f32_16x16x32_bf16 v[118:121], v[172:175], v[202:205], v[118:121]
	v_mfma_f32_16x16x32_bf16 v[114:117], v[180:183], v[202:205], v[114:117]
	v_mfma_f32_16x16x32_bf16 v[86:89], v[172:175], v[210:213], v[86:89]
	v_mfma_f32_16x16x32_bf16 v[82:85], v[180:183], v[210:213], v[82:85]
	v_mfma_f32_16x16x32_bf16 v[70:73], v[172:175], v[218:221], v[70:73]
	v_mfma_f32_16x16x32_bf16 v[66:69], v[180:183], v[218:221], v[66:69]
	s_setprio 0
	s_barrier
	s_add_i32 s68, s84, s10
	v_lshl_add_u64 v[164:165], v[164:165], 0, s[16:17]
	s_mov_b32 m0, s68
	ds_read_b128 v[190:193], v171 offset:49152
	ds_read_b128 v[194:197], v171 offset:50176
	ds_read_b128 v[198:201], v171 offset:51200
	ds_read_b128 v[202:205], v171 offset:52224
	ds_read_b128 v[206:209], v171 offset:53248
	ds_read_b128 v[210:213], v171 offset:54272
	ds_read_b128 v[214:217], v171 offset:55296
	ds_read_b128 v[218:221], v171 offset:56320
	global_load_lds_dwordx4 v[164:165], off
	s_add_i32 m0, s68, 0x2000
	s_add_u32 s30, s30, 0x40080
	v_lshl_add_u64 v[164:165], v[168:169], 0, s[16:17]
	s_addc_u32 s31, s31, 0
	s_add_i32 s68, s85, s10
	global_load_lds_dwordx4 v[164:165], off
	s_mov_b32 m0, s68
	s_nop 0
	global_load_lds_dwordx4 v148, s[30:31]
	s_add_i32 m0, s68, 0x2000
	s_nop 0
	global_load_lds_dwordx4 v152, s[30:31]
	v_lshl_add_u64 v[164:165], v[184:185], 0, s[16:17]
	s_mov_b32 m0, s61
	s_nop 0
	global_load_lds_dwordx4 v[164:165], off
	v_lshl_add_u64 v[164:165], v[222:223], 0, s[16:17]
	s_mov_b32 m0, s70
	s_nop 0
	global_load_lds_dwordx4 v[164:165], off
	s_waitcnt vmcnt(8)
	s_waitcnt lgkmcnt(0)
	s_barrier
	s_setprio 1
	s_waitcnt lgkmcnt(0)
	v_mfma_f32_16x16x32_bf16 v[60:63], v[98:101], v[190:193], v[60:63]
	v_mfma_f32_16x16x32_bf16 v[56:59], v[106:109], v[190:193], v[56:59]
	v_mfma_f32_16x16x32_bf16 v[44:47], v[98:101], v[198:201], v[44:47]
	v_mfma_f32_16x16x32_bf16 v[40:43], v[106:109], v[198:201], v[40:43]
	v_mfma_f32_16x16x32_bf16 v[28:31], v[98:101], v[206:209], v[28:31]
	v_mfma_f32_16x16x32_bf16 v[24:27], v[106:109], v[206:209], v[24:27]
	v_mfma_f32_16x16x32_bf16 v[12:15], v[98:101], v[214:217], v[12:15]
	v_mfma_f32_16x16x32_bf16 v[8:11], v[106:109], v[214:217], v[8:11]
	v_mfma_f32_16x16x32_bf16 v[60:63], v[102:105], v[194:197], v[60:63]
	v_mfma_f32_16x16x32_bf16 v[56:59], v[110:113], v[194:197], v[56:59]
	v_mfma_f32_16x16x32_bf16 v[44:47], v[102:105], v[202:205], v[44:47]
	v_mfma_f32_16x16x32_bf16 v[40:43], v[110:113], v[202:205], v[40:43]
	v_mfma_f32_16x16x32_bf16 v[28:31], v[102:105], v[210:213], v[28:31]
	v_mfma_f32_16x16x32_bf16 v[24:27], v[110:113], v[210:213], v[24:27]
	v_mfma_f32_16x16x32_bf16 v[12:15], v[102:105], v[218:221], v[12:15]
	v_mfma_f32_16x16x32_bf16 v[8:11], v[110:113], v[218:221], v[8:11]
	s_setprio 0
	s_setprio 1
	v_mfma_f32_16x16x32_bf16 v[52:55], v[160:163], v[190:193], v[52:55]
	v_mfma_f32_16x16x32_bf16 v[48:51], v[176:179], v[190:193], v[48:51]
	v_mfma_f32_16x16x32_bf16 v[36:39], v[160:163], v[198:201], v[36:39]
	v_mfma_f32_16x16x32_bf16 v[32:35], v[176:179], v[198:201], v[32:35]
	v_mfma_f32_16x16x32_bf16 v[20:23], v[160:163], v[206:209], v[20:23]
	v_mfma_f32_16x16x32_bf16 v[16:19], v[176:179], v[206:209], v[16:19]
	v_mfma_f32_16x16x32_bf16 v[4:7], v[160:163], v[214:217], v[4:7]
	v_mfma_f32_16x16x32_bf16 v[0:3], v[176:179], v[214:217], v[0:3]
	v_mfma_f32_16x16x32_bf16 v[52:55], v[172:175], v[194:197], v[52:55]
	v_mfma_f32_16x16x32_bf16 v[48:51], v[180:183], v[194:197], v[48:51]
	v_mfma_f32_16x16x32_bf16 v[36:39], v[172:175], v[202:205], v[36:39]
	v_mfma_f32_16x16x32_bf16 v[32:35], v[180:183], v[202:205], v[32:35]
	v_mfma_f32_16x16x32_bf16 v[20:23], v[172:175], v[210:213], v[20:23]
	v_mfma_f32_16x16x32_bf16 v[16:19], v[180:183], v[210:213], v[16:19]
	v_mfma_f32_16x16x32_bf16 v[4:7], v[172:175], v[218:221], v[4:7]
	v_mfma_f32_16x16x32_bf16 v[0:3], v[180:183], v[218:221], v[0:3]
	s_setprio 0
	s_barrier
	s_add_i32 s83, s83, 2
	s_add_u32 s28, s28, 0x100
	s_addc_u32 s29, s29, 0
	s_add_u32 s77, s77, 0x100
	s_addc_u32 s82, s82, 0
	s_cmp_gt_u32 s83, 13
	s_cbranch_scc0 .LBB0_893
	s_and_b64 vcc, exec, s[42:43]
	s_cbranch_vccz .LBB0_896
	s_barrier

.LBB0_1250:
	s_add_u32 s30, s28, 0xfffc0080
	s_addc_u32 s31, s29, -1
	s_add_i32 s75, 0, 0x10000
	s_cmp_eq_u32 s74, 12
	s_cselect_b32 s69, s63, s31
	s_cselect_b32 s68, s70, s30
	s_cselect_b32 s31, s49, s73
	s_cselect_b32 s30, s71, s72
	s_add_i32 s83, 0, 0x14000
	v_add_u32_e32 v110, s75, v223
	v_add_u32_e32 v170, s83, v223
	ds_read_b128 v[98:101], v110
	ds_read_b128 v[102:105], v110 offset:1024
	ds_read_b128 v[106:109], v110 offset:2048
	ds_read_b128 v[110:113], v110 offset:3072
	ds_read_b128 v[146:149], v170
	ds_read_b128 v[162:165], v170 offset:1024
	ds_read_b128 v[166:169], v170 offset:2048
	ds_read_b128 v[170:173], v170 offset:3072
	s_add_i32 m0, s0, 0xc000
	ds_read_b128 v[174:177], v225
	ds_read_b128 v[178:181], v225 offset:1024
	ds_read_b128 v[182:185], v225 offset:2048
	ds_read_b128 v[190:193], v225 offset:3072
	ds_read_b128 v[194:197], v225 offset:4096
	ds_read_b128 v[198:201], v225 offset:5120
	ds_read_b128 v[202:205], v225 offset:6144
	ds_read_b128 v[206:209], v225 offset:7168
	global_load_lds_dwordx4 v158, s[28:29]
	s_add_i32 m0, s0, 0xe000
	s_nop 0
	global_load_lds_dwordx4 v160, s[28:29]
	s_waitcnt vmcnt(8)
	s_waitcnt lgkmcnt(0)
	s_barrier
	s_setprio 1
	s_waitcnt lgkmcnt(0)
	v_mfma_f32_16x16x32_bf16 v[142:145], v[98:101], v[174:177], v[142:145]
	v_mfma_f32_16x16x32_bf16 v[138:141], v[106:109], v[174:177], v[138:141]
	v_mfma_f32_16x16x32_bf16 v[134:137], v[98:101], v[182:185], v[134:137]
	v_mfma_f32_16x16x32_bf16 v[130:133], v[106:109], v[182:185], v[130:133]
	v_mfma_f32_16x16x32_bf16 v[126:129], v[98:101], v[194:197], v[126:129]
	v_mfma_f32_16x16x32_bf16 v[122:125], v[106:109], v[194:197], v[122:125]
	v_mfma_f32_16x16x32_bf16 v[118:121], v[98:101], v[202:205], v[118:121]
	v_mfma_f32_16x16x32_bf16 v[114:117], v[106:109], v[202:205], v[114:117]
	v_mfma_f32_16x16x32_bf16 v[142:145], v[102:105], v[178:181], v[142:145]
	v_mfma_f32_16x16x32_bf16 v[138:141], v[110:113], v[178:181], v[138:141]
	v_mfma_f32_16x16x32_bf16 v[134:137], v[102:105], v[190:193], v[134:137]
	v_mfma_f32_16x16x32_bf16 v[130:133], v[110:113], v[190:193], v[130:133]
	v_mfma_f32_16x16x32_bf16 v[126:129], v[102:105], v[198:201], v[126:129]
	v_mfma_f32_16x16x32_bf16 v[122:125], v[110:113], v[198:201], v[122:125]
	v_mfma_f32_16x16x32_bf16 v[118:121], v[102:105], v[206:209], v[118:121]
	v_mfma_f32_16x16x32_bf16 v[114:117], v[110:113], v[206:209], v[114:117]
	s_setprio 0
	s_setprio 1
	v_mfma_f32_16x16x32_bf16 v[60:63], v[146:149], v[174:177], v[60:63]
	v_mfma_f32_16x16x32_bf16 v[56:59], v[166:169], v[174:177], v[56:59]
	v_mfma_f32_16x16x32_bf16 v[52:55], v[146:149], v[182:185], v[52:55]
	v_mfma_f32_16x16x32_bf16 v[48:51], v[166:169], v[182:185], v[48:51]
	v_mfma_f32_16x16x32_bf16 v[44:47], v[146:149], v[194:197], v[44:47]
	v_mfma_f32_16x16x32_bf16 v[40:43], v[166:169], v[194:197], v[40:43]
	v_mfma_f32_16x16x32_bf16 v[36:39], v[146:149], v[202:205], v[36:39]
	v_mfma_f32_16x16x32_bf16 v[32:35], v[166:169], v[202:205], v[32:35]
	v_mfma_f32_16x16x32_bf16 v[60:63], v[162:165], v[178:181], v[60:63]
	v_mfma_f32_16x16x32_bf16 v[56:59], v[170:173], v[178:181], v[56:59]
	v_mfma_f32_16x16x32_bf16 v[52:55], v[162:165], v[190:193], v[52:55]
	v_mfma_f32_16x16x32_bf16 v[48:51], v[170:173], v[190:193], v[48:51]
	v_mfma_f32_16x16x32_bf16 v[44:47], v[162:165], v[198:201], v[44:47]
	v_mfma_f32_16x16x32_bf16 v[40:43], v[170:173], v[198:201], v[40:43]
	v_mfma_f32_16x16x32_bf16 v[36:39], v[162:165], v[206:209], v[36:39]
	v_mfma_f32_16x16x32_bf16 v[32:35], v[170:173], v[206:209], v[32:35]
	s_setprio 0
	s_barrier
	s_add_i32 s75, s75, s5
	v_lshl_add_u64 v[210:211], s[30:31], 0, v[152:153]
	s_mov_b32 m0, s75
	ds_read_b128 v[174:177], v225 offset:16384
	ds_read_b128 v[178:181], v225 offset:17408
	ds_read_b128 v[182:185], v225 offset:18432
	ds_read_b128 v[190:193], v225 offset:19456
	ds_read_b128 v[194:197], v225 offset:20480
	ds_read_b128 v[198:201], v225 offset:21504
	ds_read_b128 v[202:205], v225 offset:22528
	ds_read_b128 v[206:209], v225 offset:23552
	global_load_lds_dwordx4 v152, s[30:31]
	s_add_i32 m0, s75, 0x2000
	s_add_u32 vcc_lo, s30, 0x40000
	v_lshl_add_u64 v[212:213], s[30:31], 0, v[156:157]
	s_addc_u32 vcc_hi, s31, 0
	s_add_i32 s75, s83, s5
	global_load_lds_dwordx4 v156, s[30:31]
	s_mov_b32 m0, s75
	v_lshl_add_u64 v[216:217], s[68:69], 0, v[154:155]
	global_load_lds_dwordx4 v152, vcc
	s_add_i32 m0, s75, 0x2000
	s_nop 0
	global_load_lds_dwordx4 v156, vcc
	v_lshl_add_u64 v[214:215], s[68:69], 0, v[150:151]
	s_mov_b32 m0, s0
	s_nop 0
	global_load_lds_dwordx4 v150, s[68:69]
	s_mov_b32 m0, s1
	s_nop 0
	global_load_lds_dwordx4 v154, s[68:69]
	s_waitcnt vmcnt(8)
	s_waitcnt lgkmcnt(0)
	s_barrier
	s_setprio 1
	s_waitcnt lgkmcnt(0)
	v_mfma_f32_16x16x32_bf16 v[94:97], v[98:101], v[174:177], v[94:97]
	v_mfma_f32_16x16x32_bf16 v[90:93], v[106:109], v[174:177], v[90:93]
	v_mfma_f32_16x16x32_bf16 v[86:89], v[98:101], v[182:185], v[86:89]
	v_mfma_f32_16x16x32_bf16 v[82:85], v[106:109], v[182:185], v[82:85]
	v_mfma_f32_16x16x32_bf16 v[78:81], v[98:101], v[194:197], v[78:81]
	v_mfma_f32_16x16x32_bf16 v[74:77], v[106:109], v[194:197], v[74:77]
	v_mfma_f32_16x16x32_bf16 v[70:73], v[98:101], v[202:205], v[70:73]
	v_mfma_f32_16x16x32_bf16 v[66:69], v[106:109], v[202:205], v[66:69]
	v_mfma_f32_16x16x32_bf16 v[94:97], v[102:105], v[178:181], v[94:97]
	v_mfma_f32_16x16x32_bf16 v[90:93], v[110:113], v[178:181], v[90:93]
	v_mfma_f32_16x16x32_bf16 v[86:89], v[102:105], v[190:193], v[86:89]
	v_mfma_f32_16x16x32_bf16 v[82:85], v[110:113], v[190:193], v[82:85]
	v_mfma_f32_16x16x32_bf16 v[78:81], v[102:105], v[198:201], v[78:81]
	v_mfma_f32_16x16x32_bf16 v[74:77], v[110:113], v[198:201], v[74:77]
	v_mfma_f32_16x16x32_bf16 v[70:73], v[102:105], v[206:209], v[70:73]
	v_mfma_f32_16x16x32_bf16 v[66:69], v[110:113], v[206:209], v[66:69]
	s_setprio 0
	s_setprio 1
	v_mfma_f32_16x16x32_bf16 v[28:31], v[146:149], v[174:177], v[28:31]
	v_mfma_f32_16x16x32_bf16 v[24:27], v[166:169], v[174:177], v[24:27]
	v_mfma_f32_16x16x32_bf16 v[20:23], v[146:149], v[182:185], v[20:23]
	v_mfma_f32_16x16x32_bf16 v[16:19], v[166:169], v[182:185], v[16:19]
	v_mfma_f32_16x16x32_bf16 v[12:15], v[146:149], v[194:197], v[12:15]
	v_mfma_f32_16x16x32_bf16 v[8:11], v[166:169], v[194:197], v[8:11]
	v_mfma_f32_16x16x32_bf16 v[4:7], v[146:149], v[202:205], v[4:7]
	v_mfma_f32_16x16x32_bf16 v[0:3], v[166:169], v[202:205], v[0:3]
	v_mfma_f32_16x16x32_bf16 v[28:31], v[162:165], v[178:181], v[28:31]
	v_mfma_f32_16x16x32_bf16 v[24:27], v[170:173], v[178:181], v[24:27]
	v_mfma_f32_16x16x32_bf16 v[20:23], v[162:165], v[190:193], v[20:23]
	v_mfma_f32_16x16x32_bf16 v[16:19], v[170:173], v[190:193], v[16:19]
	v_mfma_f32_16x16x32_bf16 v[12:15], v[162:165], v[198:201], v[12:15]
	v_mfma_f32_16x16x32_bf16 v[8:11], v[170:173], v[198:201], v[8:11]
	v_mfma_f32_16x16x32_bf16 v[4:7], v[162:165], v[206:209], v[4:7]
	v_mfma_f32_16x16x32_bf16 v[0:3], v[170:173], v[206:209], v[0:3]
	s_setprio 0
	s_barrier
	s_add_i32 s75, 0, 0x18000
	s_add_i32 s83, 0, 0x1c000
	v_add_u32_e32 v110, s75, v223
	v_add_u32_e32 v170, s83, v223
	ds_read_b128 v[98:101], v110
	ds_read_b128 v[102:105], v110 offset:1024
	ds_read_b128 v[106:109], v110 offset:2048
	ds_read_b128 v[110:113], v110 offset:3072
	ds_read_b128 v[146:149], v170
	ds_read_b128 v[162:165], v170 offset:1024
	ds_read_b128 v[166:169], v170 offset:2048
	ds_read_b128 v[170:173], v170 offset:3072
	s_add_u32 s68, s68, 0x40000
	s_addc_u32 s69, s69, 0
	s_mov_b32 m0, s10
	ds_read_b128 v[174:177], v225 offset:32768
	ds_read_b128 v[178:181], v225 offset:33792
	ds_read_b128 v[182:185], v225 offset:34816
	ds_read_b128 v[190:193], v225 offset:35840
	ds_read_b128 v[194:197], v225 offset:36864
	ds_read_b128 v[198:201], v225 offset:37888
	ds_read_b128 v[202:205], v225 offset:38912
	ds_read_b128 v[206:209], v225 offset:39936
	global_load_lds_dwordx4 v150, s[68:69]
	s_mov_b32 m0, s11
	s_nop 0
	global_load_lds_dwordx4 v154, s[68:69]
	s_waitcnt vmcnt(8)
	s_waitcnt lgkmcnt(0)
	s_barrier
	s_setprio 1
	s_waitcnt lgkmcnt(0)
	v_mfma_f32_16x16x32_bf16 v[142:145], v[98:101], v[174:177], v[142:145]
	v_mfma_f32_16x16x32_bf16 v[138:141], v[106:109], v[174:177], v[138:141]
	v_mfma_f32_16x16x32_bf16 v[134:137], v[98:101], v[182:185], v[134:137]
	v_mfma_f32_16x16x32_bf16 v[130:133], v[106:109], v[182:185], v[130:133]
	v_mfma_f32_16x16x32_bf16 v[126:129], v[98:101], v[194:197], v[126:129]
	v_mfma_f32_16x16x32_bf16 v[122:125], v[106:109], v[194:197], v[122:125]
	v_mfma_f32_16x16x32_bf16 v[118:121], v[98:101], v[202:205], v[118:121]
	v_mfma_f32_16x16x32_bf16 v[114:117], v[106:109], v[202:205], v[114:117]
	v_mfma_f32_16x16x32_bf16 v[142:145], v[102:105], v[178:181], v[142:145]
	v_mfma_f32_16x16x32_bf16 v[138:141], v[110:113], v[178:181], v[138:141]
	v_mfma_f32_16x16x32_bf16 v[134:137], v[102:105], v[190:193], v[134:137]
	v_mfma_f32_16x16x32_bf16 v[130:133], v[110:113], v[190:193], v[130:133]
	v_mfma_f32_16x16x32_bf16 v[126:129], v[102:105], v[198:201], v[126:129]
	v_mfma_f32_16x16x32_bf16 v[122:125], v[110:113], v[198:201], v[122:125]
	v_mfma_f32_16x16x32_bf16 v[118:121], v[102:105], v[206:209], v[118:121]
	v_mfma_f32_16x16x32_bf16 v[114:117], v[110:113], v[206:209], v[114:117]
	s_setprio 0
	s_setprio 1
	v_mfma_f32_16x16x32_bf16 v[60:63], v[146:149], v[174:177], v[60:63]
	v_mfma_f32_16x16x32_bf16 v[56:59], v[166:169], v[174:177], v[56:59]
	v_mfma_f32_16x16x32_bf16 v[52:55], v[146:149], v[182:185], v[52:55]
	v_mfma_f32_16x16x32_bf16 v[48:51], v[166:169], v[182:185], v[48:51]
	v_mfma_f32_16x16x32_bf16 v[44:47], v[146:149], v[194:197], v[44:47]
	v_mfma_f32_16x16x32_bf16 v[40:43], v[166:169], v[194:197], v[40:43]
	v_mfma_f32_16x16x32_bf16 v[36:39], v[146:149], v[202:205], v[36:39]
	v_mfma_f32_16x16x32_bf16 v[32:35], v[166:169], v[202:205], v[32:35]
	v_mfma_f32_16x16x32_bf16 v[60:63], v[162:165], v[178:181], v[60:63]
	v_mfma_f32_16x16x32_bf16 v[56:59], v[170:173], v[178:181], v[56:59]
	v_mfma_f32_16x16x32_bf16 v[52:55], v[162:165], v[190:193], v[52:55]
	v_mfma_f32_16x16x32_bf16 v[48:51], v[170:173], v[190:193], v[48:51]
	v_mfma_f32_16x16x32_bf16 v[44:47], v[162:165], v[198:201], v[44:47]
	v_mfma_f32_16x16x32_bf16 v[40:43], v[170:173], v[198:201], v[40:43]
	v_mfma_f32_16x16x32_bf16 v[36:39], v[162:165], v[206:209], v[36:39]
	v_mfma_f32_16x16x32_bf16 v[32:35], v[170:173], v[206:209], v[32:35]
	s_setprio 0
	s_barrier
	s_add_i32 s68, s75, s5
	v_lshl_add_u64 v[210:211], v[210:211], 0, s[16:17]
	s_mov_b32 m0, s68
	ds_read_b128 v[174:177], v225 offset:49152
	ds_read_b128 v[178:181], v225 offset:50176
	ds_read_b128 v[182:185], v225 offset:51200
	ds_read_b128 v[190:193], v225 offset:52224
	ds_read_b128 v[194:197], v225 offset:53248
	ds_read_b128 v[198:201], v225 offset:54272
	ds_read_b128 v[202:205], v225 offset:55296
	ds_read_b128 v[206:209], v225 offset:56320
	global_load_lds_dwordx4 v[210:211], off
	s_add_i32 m0, s68, 0x2000
	s_add_u32 s30, s30, 0x40080
	v_lshl_add_u64 v[210:211], v[212:213], 0, s[16:17]
	s_addc_u32 s31, s31, 0
	s_add_i32 s68, s83, s5
	global_load_lds_dwordx4 v[210:211], off
	s_mov_b32 m0, s68
	s_nop 0
	global_load_lds_dwordx4 v152, s[30:31]
	s_add_i32 m0, s68, 0x2000
	s_nop 0
	global_load_lds_dwordx4 v156, s[30:31]
	v_lshl_add_u64 v[210:211], v[214:215], 0, s[16:17]
	s_mov_b32 m0, s4
	s_nop 0
	global_load_lds_dwordx4 v[210:211], off
	v_lshl_add_u64 v[210:211], v[216:217], 0, s[16:17]
	s_mov_b32 m0, s90
	s_nop 0
	global_load_lds_dwordx4 v[210:211], off
	s_waitcnt vmcnt(8)
	s_waitcnt lgkmcnt(0)
	s_barrier
	s_setprio 1
	s_waitcnt lgkmcnt(0)
	v_mfma_f32_16x16x32_bf16 v[94:97], v[98:101], v[174:177], v[94:97]
	v_mfma_f32_16x16x32_bf16 v[90:93], v[106:109], v[174:177], v[90:93]
	v_mfma_f32_16x16x32_bf16 v[86:89], v[98:101], v[182:185], v[86:89]
	v_mfma_f32_16x16x32_bf16 v[82:85], v[106:109], v[182:185], v[82:85]
	v_mfma_f32_16x16x32_bf16 v[78:81], v[98:101], v[194:197], v[78:81]
	v_mfma_f32_16x16x32_bf16 v[74:77], v[106:109], v[194:197], v[74:77]
	v_mfma_f32_16x16x32_bf16 v[70:73], v[98:101], v[202:205], v[70:73]
	v_mfma_f32_16x16x32_bf16 v[66:69], v[106:109], v[202:205], v[66:69]
	v_mfma_f32_16x16x32_bf16 v[94:97], v[102:105], v[178:181], v[94:97]
	v_mfma_f32_16x16x32_bf16 v[90:93], v[110:113], v[178:181], v[90:93]
	v_mfma_f32_16x16x32_bf16 v[86:89], v[102:105], v[190:193], v[86:89]
	v_mfma_f32_16x16x32_bf16 v[82:85], v[110:113], v[190:193], v[82:85]
	v_mfma_f32_16x16x32_bf16 v[78:81], v[102:105], v[198:201], v[78:81]
	v_mfma_f32_16x16x32_bf16 v[74:77], v[110:113], v[198:201], v[74:77]
	v_mfma_f32_16x16x32_bf16 v[70:73], v[102:105], v[206:209], v[70:73]
	v_mfma_f32_16x16x32_bf16 v[66:69], v[110:113], v[206:209], v[66:69]
	s_setprio 0
	s_setprio 1
	v_mfma_f32_16x16x32_bf16 v[28:31], v[146:149], v[174:177], v[28:31]
	v_mfma_f32_16x16x32_bf16 v[24:27], v[166:169], v[174:177], v[24:27]
	v_mfma_f32_16x16x32_bf16 v[20:23], v[146:149], v[182:185], v[20:23]
	v_mfma_f32_16x16x32_bf16 v[16:19], v[166:169], v[182:185], v[16:19]
	v_mfma_f32_16x16x32_bf16 v[12:15], v[146:149], v[194:197], v[12:15]
	v_mfma_f32_16x16x32_bf16 v[8:11], v[166:169], v[194:197], v[8:11]
	v_mfma_f32_16x16x32_bf16 v[4:7], v[146:149], v[202:205], v[4:7]
	v_mfma_f32_16x16x32_bf16 v[0:3], v[166:169], v[202:205], v[0:3]
	v_mfma_f32_16x16x32_bf16 v[28:31], v[162:165], v[178:181], v[28:31]
	v_mfma_f32_16x16x32_bf16 v[24:27], v[170:173], v[178:181], v[24:27]
	v_mfma_f32_16x16x32_bf16 v[20:23], v[162:165], v[190:193], v[20:23]
	v_mfma_f32_16x16x32_bf16 v[16:19], v[170:173], v[190:193], v[16:19]
	v_mfma_f32_16x16x32_bf16 v[12:15], v[162:165], v[198:201], v[12:15]
	v_mfma_f32_16x16x32_bf16 v[8:11], v[170:173], v[198:201], v[8:11]
	v_mfma_f32_16x16x32_bf16 v[4:7], v[162:165], v[206:209], v[4:7]
	v_mfma_f32_16x16x32_bf16 v[0:3], v[170:173], v[206:209], v[0:3]
	s_setprio 0
	s_barrier
	s_add_i32 s74, s74, 2
	s_add_u32 s28, s28, 0x100
	s_addc_u32 s29, s29, 0
	s_add_u32 s72, s72, 0x100
	s_addc_u32 s73, s73, 0
	s_cmp_gt_u32 s74, 13
	s_cbranch_scc0 .LBB0_1250
	s_and_b64 vcc, exec, s[44:45]
	s_cbranch_vccz .LBB0_1253
	s_barrier

.LBB0_1384:
	s_add_u32 s68, s30, 0xfffc0080
	s_addc_u32 s69, s31, -1
	s_add_i32 s77, 0, 0x10000
	s_cmp_eq_u32 s76, 12
	s_cselect_b32 s71, s49, s69
	s_cselect_b32 s70, s72, s68
	s_cselect_b32 s69, s45, s75
	s_cselect_b32 s68, s73, s74
	s_add_i32 s84, 0, 0x14000
	v_add_u32_e32 v126, s77, v162
	v_add_u32_e32 v165, s84, v162
	ds_read_b128 v[114:117], v126
	ds_read_b128 v[118:121], v126 offset:1024
	ds_read_b128 v[122:125], v126 offset:2048
	ds_read_b128 v[126:129], v126 offset:3072
	ds_read_b128 v[158:161], v165
	ds_read_b128 v[166:169], v165 offset:1024
	ds_read_b128 v[170:173], v165 offset:2048
	ds_read_b128 v[174:177], v165 offset:3072
	s_add_i32 m0, s11, 0xc000
	ds_read_b128 v[178:181], v164
	ds_read_b128 v[182:185], v164 offset:1024
	ds_read_b128 v[190:193], v164 offset:2048
	ds_read_b128 v[194:197], v164 offset:3072
	ds_read_b128 v[198:201], v164 offset:4096
	ds_read_b128 v[202:205], v164 offset:5120
	ds_read_b128 v[206:209], v164 offset:6144
	ds_read_b128 v[210:213], v164 offset:7168
	global_load_lds_dwordx4 v154, s[30:31]
	s_add_i32 m0, s11, 0xe000
	s_nop 0
	global_load_lds_dwordx4 v156, s[30:31]
	s_waitcnt vmcnt(8)
	s_waitcnt lgkmcnt(0)
	s_barrier
	s_setprio 1
	s_waitcnt lgkmcnt(0)
	v_mfma_f32_16x16x32_bf16 v[142:145], v[114:117], v[178:181], v[142:145]
	v_mfma_f32_16x16x32_bf16 v[138:141], v[122:125], v[178:181], v[138:141]
	v_mfma_f32_16x16x32_bf16 v[110:113], v[114:117], v[190:193], v[110:113]
	v_mfma_f32_16x16x32_bf16 v[106:109], v[122:125], v[190:193], v[106:109]
	v_mfma_f32_16x16x32_bf16 v[94:97], v[114:117], v[198:201], v[94:97]
	v_mfma_f32_16x16x32_bf16 v[90:93], v[122:125], v[198:201], v[90:93]
	v_mfma_f32_16x16x32_bf16 v[78:81], v[114:117], v[206:209], v[78:81]
	v_mfma_f32_16x16x32_bf16 v[74:77], v[122:125], v[206:209], v[74:77]
	v_mfma_f32_16x16x32_bf16 v[142:145], v[118:121], v[182:185], v[142:145]
	v_mfma_f32_16x16x32_bf16 v[138:141], v[126:129], v[182:185], v[138:141]
	v_mfma_f32_16x16x32_bf16 v[110:113], v[118:121], v[194:197], v[110:113]
	v_mfma_f32_16x16x32_bf16 v[106:109], v[126:129], v[194:197], v[106:109]
	v_mfma_f32_16x16x32_bf16 v[94:97], v[118:121], v[202:205], v[94:97]
	v_mfma_f32_16x16x32_bf16 v[90:93], v[126:129], v[202:205], v[90:93]
	v_mfma_f32_16x16x32_bf16 v[78:81], v[118:121], v[210:213], v[78:81]
	v_mfma_f32_16x16x32_bf16 v[74:77], v[126:129], v[210:213], v[74:77]
	s_setprio 0
	s_setprio 1
	v_mfma_f32_16x16x32_bf16 v[134:137], v[158:161], v[178:181], v[134:137]
	v_mfma_f32_16x16x32_bf16 v[130:133], v[170:173], v[178:181], v[130:133]
	v_mfma_f32_16x16x32_bf16 v[102:105], v[158:161], v[190:193], v[102:105]
	v_mfma_f32_16x16x32_bf16 v[98:101], v[170:173], v[190:193], v[98:101]
	v_mfma_f32_16x16x32_bf16 v[86:89], v[158:161], v[198:201], v[86:89]
	v_mfma_f32_16x16x32_bf16 v[82:85], v[170:173], v[198:201], v[82:85]
	v_mfma_f32_16x16x32_bf16 v[70:73], v[158:161], v[206:209], v[70:73]
	v_mfma_f32_16x16x32_bf16 v[66:69], v[170:173], v[206:209], v[66:69]
	v_mfma_f32_16x16x32_bf16 v[134:137], v[166:169], v[182:185], v[134:137]
	v_mfma_f32_16x16x32_bf16 v[130:133], v[174:177], v[182:185], v[130:133]
	v_mfma_f32_16x16x32_bf16 v[102:105], v[166:169], v[194:197], v[102:105]
	v_mfma_f32_16x16x32_bf16 v[98:101], v[174:177], v[194:197], v[98:101]
	v_mfma_f32_16x16x32_bf16 v[86:89], v[166:169], v[202:205], v[86:89]
	v_mfma_f32_16x16x32_bf16 v[82:85], v[174:177], v[202:205], v[82:85]
	v_mfma_f32_16x16x32_bf16 v[70:73], v[166:169], v[210:213], v[70:73]
	v_mfma_f32_16x16x32_bf16 v[66:69], v[174:177], v[210:213], v[66:69]
	s_setprio 0
	s_barrier
	s_add_i32 s77, s77, s10
	v_lshl_add_u64 v[214:215], s[68:69], 0, v[148:149]
	s_mov_b32 m0, s77
	ds_read_b128 v[178:181], v164 offset:16384
	ds_read_b128 v[182:185], v164 offset:17408
	ds_read_b128 v[190:193], v164 offset:18432
	ds_read_b128 v[194:197], v164 offset:19456
	ds_read_b128 v[198:201], v164 offset:20480
	ds_read_b128 v[202:205], v164 offset:21504
	ds_read_b128 v[206:209], v164 offset:22528
	ds_read_b128 v[210:213], v164 offset:23552
	global_load_lds_dwordx4 v148, s[68:69]
	s_add_i32 m0, s77, 0x2000
	s_add_u32 s82, s68, 0x40000
	v_lshl_add_u64 v[216:217], s[68:69], 0, v[152:153]
	s_addc_u32 s83, s69, 0
	s_add_i32 s77, s84, s10
	global_load_lds_dwordx4 v152, s[68:69]
	s_mov_b32 m0, s77
	v_lshl_add_u64 v[220:221], s[70:71], 0, v[150:151]
	global_load_lds_dwordx4 v148, s[82:83]
	s_add_i32 m0, s77, 0x2000
	s_nop 0
	global_load_lds_dwordx4 v152, s[82:83]
	v_lshl_add_u64 v[218:219], s[70:71], 0, v[146:147]
	s_mov_b32 m0, s11
	s_nop 0
	global_load_lds_dwordx4 v146, s[70:71]
	s_mov_b32 m0, s13
	s_nop 0
	global_load_lds_dwordx4 v150, s[70:71]
	s_waitcnt vmcnt(8)
	s_waitcnt lgkmcnt(0)
	s_barrier
	s_setprio 1
	s_waitcnt lgkmcnt(0)
	v_mfma_f32_16x16x32_bf16 v[60:63], v[114:117], v[178:181], v[60:63]
	v_mfma_f32_16x16x32_bf16 v[56:59], v[122:125], v[178:181], v[56:59]
	v_mfma_f32_16x16x32_bf16 v[44:47], v[114:117], v[190:193], v[44:47]
	v_mfma_f32_16x16x32_bf16 v[40:43], v[122:125], v[190:193], v[40:43]
	v_mfma_f32_16x16x32_bf16 v[28:31], v[114:117], v[198:201], v[28:31]
	v_mfma_f32_16x16x32_bf16 v[24:27], v[122:125], v[198:201], v[24:27]
	v_mfma_f32_16x16x32_bf16 v[12:15], v[114:117], v[206:209], v[12:15]
	v_mfma_f32_16x16x32_bf16 v[8:11], v[122:125], v[206:209], v[8:11]
	v_mfma_f32_16x16x32_bf16 v[60:63], v[118:121], v[182:185], v[60:63]
	v_mfma_f32_16x16x32_bf16 v[56:59], v[126:129], v[182:185], v[56:59]
	v_mfma_f32_16x16x32_bf16 v[44:47], v[118:121], v[194:197], v[44:47]
	v_mfma_f32_16x16x32_bf16 v[40:43], v[126:129], v[194:197], v[40:43]
	v_mfma_f32_16x16x32_bf16 v[28:31], v[118:121], v[202:205], v[28:31]
	v_mfma_f32_16x16x32_bf16 v[24:27], v[126:129], v[202:205], v[24:27]
	v_mfma_f32_16x16x32_bf16 v[12:15], v[118:121], v[210:213], v[12:15]
	v_mfma_f32_16x16x32_bf16 v[8:11], v[126:129], v[210:213], v[8:11]
	s_setprio 0
	s_setprio 1
	v_mfma_f32_16x16x32_bf16 v[52:55], v[158:161], v[178:181], v[52:55]
	v_mfma_f32_16x16x32_bf16 v[48:51], v[170:173], v[178:181], v[48:51]
	v_mfma_f32_16x16x32_bf16 v[36:39], v[158:161], v[190:193], v[36:39]
	v_mfma_f32_16x16x32_bf16 v[32:35], v[170:173], v[190:193], v[32:35]
	v_mfma_f32_16x16x32_bf16 v[20:23], v[158:161], v[198:201], v[20:23]
	v_mfma_f32_16x16x32_bf16 v[16:19], v[170:173], v[198:201], v[16:19]
	v_mfma_f32_16x16x32_bf16 v[4:7], v[158:161], v[206:209], v[4:7]
	v_mfma_f32_16x16x32_bf16 v[0:3], v[170:173], v[206:209], v[0:3]
	v_mfma_f32_16x16x32_bf16 v[52:55], v[166:169], v[182:185], v[52:55]
	v_mfma_f32_16x16x32_bf16 v[48:51], v[174:177], v[182:185], v[48:51]
	v_mfma_f32_16x16x32_bf16 v[36:39], v[166:169], v[194:197], v[36:39]
	v_mfma_f32_16x16x32_bf16 v[32:35], v[174:177], v[194:197], v[32:35]
	v_mfma_f32_16x16x32_bf16 v[20:23], v[166:169], v[202:205], v[20:23]
	v_mfma_f32_16x16x32_bf16 v[16:19], v[174:177], v[202:205], v[16:19]
	v_mfma_f32_16x16x32_bf16 v[4:7], v[166:169], v[210:213], v[4:7]
	v_mfma_f32_16x16x32_bf16 v[0:3], v[174:177], v[210:213], v[0:3]
	s_setprio 0
	s_barrier
	s_add_i32 s77, 0, 0x18000
	s_add_i32 s82, 0, 0x1c000
	v_add_u32_e32 v126, s77, v162
	v_add_u32_e32 v165, s82, v162
	ds_read_b128 v[114:117], v126
	ds_read_b128 v[118:121], v126 offset:1024
	ds_read_b128 v[122:125], v126 offset:2048
	ds_read_b128 v[126:129], v126 offset:3072
	ds_read_b128 v[158:161], v165
	ds_read_b128 v[166:169], v165 offset:1024
	ds_read_b128 v[170:173], v165 offset:2048
	ds_read_b128 v[174:177], v165 offset:3072
	s_add_u32 s70, s70, 0x40000
	s_addc_u32 s71, s71, 0
	s_mov_b32 m0, s19
	ds_read_b128 v[178:181], v164 offset:32768
	ds_read_b128 v[182:185], v164 offset:33792
	ds_read_b128 v[190:193], v164 offset:34816
	ds_read_b128 v[194:197], v164 offset:35840
	ds_read_b128 v[198:201], v164 offset:36864
	ds_read_b128 v[202:205], v164 offset:37888
	ds_read_b128 v[206:209], v164 offset:38912
	ds_read_b128 v[210:213], v164 offset:39936
	global_load_lds_dwordx4 v146, s[70:71]
	s_mov_b32 m0, s34
	s_nop 0
	global_load_lds_dwordx4 v150, s[70:71]
	s_waitcnt vmcnt(8)
	s_waitcnt lgkmcnt(0)
	s_barrier
	s_setprio 1
	s_waitcnt lgkmcnt(0)
	v_mfma_f32_16x16x32_bf16 v[142:145], v[114:117], v[178:181], v[142:145]
	v_mfma_f32_16x16x32_bf16 v[138:141], v[122:125], v[178:181], v[138:141]
	v_mfma_f32_16x16x32_bf16 v[110:113], v[114:117], v[190:193], v[110:113]
	v_mfma_f32_16x16x32_bf16 v[106:109], v[122:125], v[190:193], v[106:109]
	v_mfma_f32_16x16x32_bf16 v[94:97], v[114:117], v[198:201], v[94:97]
	v_mfma_f32_16x16x32_bf16 v[90:93], v[122:125], v[198:201], v[90:93]
	v_mfma_f32_16x16x32_bf16 v[78:81], v[114:117], v[206:209], v[78:81]
	v_mfma_f32_16x16x32_bf16 v[74:77], v[122:125], v[206:209], v[74:77]
	v_mfma_f32_16x16x32_bf16 v[142:145], v[118:121], v[182:185], v[142:145]
	v_mfma_f32_16x16x32_bf16 v[138:141], v[126:129], v[182:185], v[138:141]
	v_mfma_f32_16x16x32_bf16 v[110:113], v[118:121], v[194:197], v[110:113]
	v_mfma_f32_16x16x32_bf16 v[106:109], v[126:129], v[194:197], v[106:109]
	v_mfma_f32_16x16x32_bf16 v[94:97], v[118:121], v[202:205], v[94:97]
	v_mfma_f32_16x16x32_bf16 v[90:93], v[126:129], v[202:205], v[90:93]
	v_mfma_f32_16x16x32_bf16 v[78:81], v[118:121], v[210:213], v[78:81]
	v_mfma_f32_16x16x32_bf16 v[74:77], v[126:129], v[210:213], v[74:77]
	s_setprio 0
	s_setprio 1
	v_mfma_f32_16x16x32_bf16 v[134:137], v[158:161], v[178:181], v[134:137]
	v_mfma_f32_16x16x32_bf16 v[130:133], v[170:173], v[178:181], v[130:133]
	v_mfma_f32_16x16x32_bf16 v[102:105], v[158:161], v[190:193], v[102:105]
	v_mfma_f32_16x16x32_bf16 v[98:101], v[170:173], v[190:193], v[98:101]
	v_mfma_f32_16x16x32_bf16 v[86:89], v[158:161], v[198:201], v[86:89]
	v_mfma_f32_16x16x32_bf16 v[82:85], v[170:173], v[198:201], v[82:85]
	v_mfma_f32_16x16x32_bf16 v[70:73], v[158:161], v[206:209], v[70:73]
	v_mfma_f32_16x16x32_bf16 v[66:69], v[170:173], v[206:209], v[66:69]
	v_mfma_f32_16x16x32_bf16 v[134:137], v[166:169], v[182:185], v[134:137]
	v_mfma_f32_16x16x32_bf16 v[130:133], v[174:177], v[182:185], v[130:133]
	v_mfma_f32_16x16x32_bf16 v[102:105], v[166:169], v[194:197], v[102:105]
	v_mfma_f32_16x16x32_bf16 v[98:101], v[174:177], v[194:197], v[98:101]
	v_mfma_f32_16x16x32_bf16 v[86:89], v[166:169], v[202:205], v[86:89]
	v_mfma_f32_16x16x32_bf16 v[82:85], v[174:177], v[202:205], v[82:85]
	v_mfma_f32_16x16x32_bf16 v[70:73], v[166:169], v[210:213], v[70:73]
	v_mfma_f32_16x16x32_bf16 v[66:69], v[174:177], v[210:213], v[66:69]
	s_setprio 0
	s_barrier
	s_add_i32 s70, s77, s10
	v_lshl_add_u64 v[214:215], v[214:215], 0, s[16:17]
	s_mov_b32 m0, s70
	ds_read_b128 v[178:181], v164 offset:49152
	ds_read_b128 v[182:185], v164 offset:50176
	ds_read_b128 v[190:193], v164 offset:51200
	ds_read_b128 v[194:197], v164 offset:52224
	ds_read_b128 v[198:201], v164 offset:53248
	ds_read_b128 v[202:205], v164 offset:54272
	ds_read_b128 v[206:209], v164 offset:55296
	ds_read_b128 v[210:213], v164 offset:56320
	global_load_lds_dwordx4 v[214:215], off
	s_add_i32 m0, s70, 0x2000
	s_add_u32 s68, s68, 0x40080
	v_lshl_add_u64 v[214:215], v[216:217], 0, s[16:17]
	s_addc_u32 s69, s69, 0
	s_add_i32 s70, s82, s10
	global_load_lds_dwordx4 v[214:215], off
	s_mov_b32 m0, s70
	s_nop 0
	global_load_lds_dwordx4 v148, s[68:69]
	s_add_i32 m0, s70, 0x2000
	s_nop 0
	global_load_lds_dwordx4 v152, s[68:69]
	v_lshl_add_u64 v[214:215], v[218:219], 0, s[16:17]
	s_mov_b32 m0, s47
	s_nop 0
	global_load_lds_dwordx4 v[214:215], off
	v_lshl_add_u64 v[214:215], v[220:221], 0, s[16:17]
	s_mov_b32 m0, s61
	s_nop 0
	global_load_lds_dwordx4 v[214:215], off
	s_waitcnt vmcnt(8)
	s_waitcnt lgkmcnt(0)
	s_barrier
	s_setprio 1
	s_waitcnt lgkmcnt(0)
	v_mfma_f32_16x16x32_bf16 v[60:63], v[114:117], v[178:181], v[60:63]
	v_mfma_f32_16x16x32_bf16 v[56:59], v[122:125], v[178:181], v[56:59]
	v_mfma_f32_16x16x32_bf16 v[44:47], v[114:117], v[190:193], v[44:47]
	v_mfma_f32_16x16x32_bf16 v[40:43], v[122:125], v[190:193], v[40:43]
	v_mfma_f32_16x16x32_bf16 v[28:31], v[114:117], v[198:201], v[28:31]
	v_mfma_f32_16x16x32_bf16 v[24:27], v[122:125], v[198:201], v[24:27]
	v_mfma_f32_16x16x32_bf16 v[12:15], v[114:117], v[206:209], v[12:15]
	v_mfma_f32_16x16x32_bf16 v[8:11], v[122:125], v[206:209], v[8:11]
	v_mfma_f32_16x16x32_bf16 v[60:63], v[118:121], v[182:185], v[60:63]
	v_mfma_f32_16x16x32_bf16 v[56:59], v[126:129], v[182:185], v[56:59]
	v_mfma_f32_16x16x32_bf16 v[44:47], v[118:121], v[194:197], v[44:47]
	v_mfma_f32_16x16x32_bf16 v[40:43], v[126:129], v[194:197], v[40:43]
	v_mfma_f32_16x16x32_bf16 v[28:31], v[118:121], v[202:205], v[28:31]
	v_mfma_f32_16x16x32_bf16 v[24:27], v[126:129], v[202:205], v[24:27]
	v_mfma_f32_16x16x32_bf16 v[12:15], v[118:121], v[210:213], v[12:15]
	v_mfma_f32_16x16x32_bf16 v[8:11], v[126:129], v[210:213], v[8:11]
	s_setprio 0
	s_setprio 1
	v_mfma_f32_16x16x32_bf16 v[52:55], v[158:161], v[178:181], v[52:55]
	v_mfma_f32_16x16x32_bf16 v[48:51], v[170:173], v[178:181], v[48:51]
	v_mfma_f32_16x16x32_bf16 v[36:39], v[158:161], v[190:193], v[36:39]
	v_mfma_f32_16x16x32_bf16 v[32:35], v[170:173], v[190:193], v[32:35]
	v_mfma_f32_16x16x32_bf16 v[20:23], v[158:161], v[198:201], v[20:23]
	v_mfma_f32_16x16x32_bf16 v[16:19], v[170:173], v[198:201], v[16:19]
	v_mfma_f32_16x16x32_bf16 v[4:7], v[158:161], v[206:209], v[4:7]
	v_mfma_f32_16x16x32_bf16 v[0:3], v[170:173], v[206:209], v[0:3]
	v_mfma_f32_16x16x32_bf16 v[52:55], v[166:169], v[182:185], v[52:55]
	v_mfma_f32_16x16x32_bf16 v[48:51], v[174:177], v[182:185], v[48:51]
	v_mfma_f32_16x16x32_bf16 v[36:39], v[166:169], v[194:197], v[36:39]
	v_mfma_f32_16x16x32_bf16 v[32:35], v[174:177], v[194:197], v[32:35]
	v_mfma_f32_16x16x32_bf16 v[20:23], v[166:169], v[202:205], v[20:23]
	v_mfma_f32_16x16x32_bf16 v[16:19], v[174:177], v[202:205], v[16:19]
	v_mfma_f32_16x16x32_bf16 v[4:7], v[166:169], v[210:213], v[4:7]
	v_mfma_f32_16x16x32_bf16 v[0:3], v[174:177], v[210:213], v[0:3]
	s_setprio 0
	s_barrier
	s_add_i32 s76, s76, 2
	s_add_u32 s30, s30, 0x100
	s_addc_u32 s31, s31, 0
	s_add_u32 s74, s74, 0x100
	s_addc_u32 s75, s75, 0
	s_cmp_gt_u32 s76, 13
	s_cbranch_scc0 .LBB0_1384
	s_and_b64 vcc, exec, s[42:43]
	s_cbranch_vccz .LBB0_1387
	s_barrier

.LBB0_1461:
	s_add_u32 s30, s28, 0xfff00080
	s_addc_u32 s31, s29, -1
	s_add_i32 s84, 0, 0x10000
	s_cmp_eq_u32 s91, 60
	s_cselect_b32 s49, s35, s31
	s_cselect_b32 s48, s47, s30
	s_cselect_b32 s31, s69, s83
	s_cselect_b32 s30, s71, s82
	s_add_i32 s92, 0, 0x14000
	v_add_u32_e32 v138, s84, v246
	v_add_u32_e32 v158, s92, v246
	ds_read_b128 v[114:117], v138
	ds_read_b128 v[118:121], v138 offset:1024
	ds_read_b128 v[130:133], v138 offset:2048
	ds_read_b128 v[138:141], v138 offset:3072
	ds_read_b128 v[146:149], v158
	ds_read_b128 v[150:153], v158 offset:1024
	ds_read_b128 v[154:157], v158 offset:2048
	ds_read_b128 v[158:161], v158 offset:3072
	s_add_i32 m0, s11, 0xc000
	ds_read_b128 v[162:165], v251
	ds_read_b128 v[166:169], v251 offset:1024
	ds_read_b128 v[170:173], v251 offset:2048
	ds_read_b128 v[174:177], v251 offset:3072
	ds_read_b128 v[178:181], v251 offset:4096
	ds_read_b128 v[182:185], v251 offset:5120
	ds_read_b128 v[202:205], v251 offset:6144
	ds_read_b128 v[206:209], v251 offset:7168
	global_load_lds_dwordx4 v198, s[28:29]
	s_add_i32 m0, s11, 0xe000
	s_nop 0
	global_load_lds_dwordx4 v200, s[28:29]
	s_waitcnt vmcnt(8)
	s_waitcnt lgkmcnt(0)
	s_barrier
	s_setprio 1
	s_waitcnt lgkmcnt(0)
	v_mfma_f32_16x16x32_bf16 v[126:129], v[114:117], v[162:165], v[126:129]
	v_mfma_f32_16x16x32_bf16 v[122:125], v[130:133], v[162:165], v[122:125]
	v_mfma_f32_16x16x32_bf16 v[110:113], v[114:117], v[170:173], v[110:113]
	v_mfma_f32_16x16x32_bf16 v[106:109], v[130:133], v[170:173], v[106:109]
	v_mfma_f32_16x16x32_bf16 v[94:97], v[114:117], v[178:181], v[94:97]
	v_mfma_f32_16x16x32_bf16 v[90:93], v[130:133], v[178:181], v[90:93]
	v_mfma_f32_16x16x32_bf16 v[78:81], v[114:117], v[202:205], v[78:81]
	v_mfma_f32_16x16x32_bf16 v[74:77], v[130:133], v[202:205], v[74:77]
	v_mfma_f32_16x16x32_bf16 v[126:129], v[118:121], v[166:169], v[126:129]
	v_mfma_f32_16x16x32_bf16 v[122:125], v[138:141], v[166:169], v[122:125]
	v_mfma_f32_16x16x32_bf16 v[110:113], v[118:121], v[174:177], v[110:113]
	v_mfma_f32_16x16x32_bf16 v[106:109], v[138:141], v[174:177], v[106:109]
	v_mfma_f32_16x16x32_bf16 v[94:97], v[118:121], v[182:185], v[94:97]
	v_mfma_f32_16x16x32_bf16 v[90:93], v[138:141], v[182:185], v[90:93]
	v_mfma_f32_16x16x32_bf16 v[78:81], v[118:121], v[206:209], v[78:81]
	v_mfma_f32_16x16x32_bf16 v[74:77], v[138:141], v[206:209], v[74:77]
	s_setprio 0
	s_setprio 1
	v_mfma_f32_16x16x32_bf16 v[142:145], v[146:149], v[162:165], v[142:145]
	v_mfma_f32_16x16x32_bf16 v[134:137], v[154:157], v[162:165], v[134:137]
	v_mfma_f32_16x16x32_bf16 v[102:105], v[146:149], v[170:173], v[102:105]
	v_mfma_f32_16x16x32_bf16 v[98:101], v[154:157], v[170:173], v[98:101]
	v_mfma_f32_16x16x32_bf16 v[86:89], v[146:149], v[178:181], v[86:89]
	v_mfma_f32_16x16x32_bf16 v[82:85], v[154:157], v[178:181], v[82:85]
	v_mfma_f32_16x16x32_bf16 v[70:73], v[146:149], v[202:205], v[70:73]
	v_mfma_f32_16x16x32_bf16 v[66:69], v[154:157], v[202:205], v[66:69]
	v_mfma_f32_16x16x32_bf16 v[142:145], v[150:153], v[166:169], v[142:145]
	v_mfma_f32_16x16x32_bf16 v[134:137], v[158:161], v[166:169], v[134:137]
	v_mfma_f32_16x16x32_bf16 v[102:105], v[150:153], v[174:177], v[102:105]
	v_mfma_f32_16x16x32_bf16 v[98:101], v[158:161], v[174:177], v[98:101]
	v_mfma_f32_16x16x32_bf16 v[86:89], v[150:153], v[182:185], v[86:89]
	v_mfma_f32_16x16x32_bf16 v[82:85], v[158:161], v[182:185], v[82:85]
	v_mfma_f32_16x16x32_bf16 v[70:73], v[150:153], v[206:209], v[70:73]
	v_mfma_f32_16x16x32_bf16 v[66:69], v[158:161], v[206:209], v[66:69]
	s_setprio 0
	s_barrier
	s_add_i32 s84, s84, s10
	v_lshl_add_u64 v[210:211], s[30:31], 0, v[192:193]
	s_mov_b32 m0, s84
	ds_read_b128 v[162:165], v251 offset:16384
	ds_read_b128 v[166:169], v251 offset:17408
	ds_read_b128 v[170:173], v251 offset:18432
	ds_read_b128 v[174:177], v251 offset:19456
	ds_read_b128 v[178:181], v251 offset:20480
	ds_read_b128 v[182:185], v251 offset:21504
	ds_read_b128 v[202:205], v251 offset:22528
	ds_read_b128 v[206:209], v251 offset:23552
	global_load_lds_dwordx4 v192, s[30:31]
	s_add_i32 m0, s84, 0x2000
	s_add_u32 s84, s30, 0x100000
	v_lshl_add_u64 v[212:213], s[30:31], 0, v[196:197]
	s_addc_u32 s85, s31, 0
	s_add_i32 s92, s92, s10
	global_load_lds_dwordx4 v196, s[30:31]
	s_mov_b32 m0, s92
	v_lshl_add_u64 v[216:217], s[48:49], 0, v[194:195]
	global_load_lds_dwordx4 v192, s[84:85]
	s_add_i32 m0, s92, 0x2000
	s_nop 0
	global_load_lds_dwordx4 v196, s[84:85]
	v_lshl_add_u64 v[214:215], s[48:49], 0, v[190:191]
	s_mov_b32 m0, s11
	s_nop 0
	global_load_lds_dwordx4 v190, s[48:49]
	s_mov_b32 m0, s13
	s_nop 0
	global_load_lds_dwordx4 v194, s[48:49]
	s_waitcnt vmcnt(8)
	s_waitcnt lgkmcnt(0)
	s_barrier
	s_setprio 1
	s_waitcnt lgkmcnt(0)
	v_mfma_f32_16x16x32_bf16 v[60:63], v[114:117], v[162:165], v[60:63]
	v_mfma_f32_16x16x32_bf16 v[56:59], v[130:133], v[162:165], v[56:59]
	v_mfma_f32_16x16x32_bf16 v[44:47], v[114:117], v[170:173], v[44:47]
	v_mfma_f32_16x16x32_bf16 v[40:43], v[130:133], v[170:173], v[40:43]
	v_mfma_f32_16x16x32_bf16 v[28:31], v[114:117], v[178:181], v[28:31]
	v_mfma_f32_16x16x32_bf16 v[24:27], v[130:133], v[178:181], v[24:27]
	v_mfma_f32_16x16x32_bf16 v[12:15], v[114:117], v[202:205], v[12:15]
	v_mfma_f32_16x16x32_bf16 v[8:11], v[130:133], v[202:205], v[8:11]
	v_mfma_f32_16x16x32_bf16 v[60:63], v[118:121], v[166:169], v[60:63]
	v_mfma_f32_16x16x32_bf16 v[56:59], v[138:141], v[166:169], v[56:59]
	v_mfma_f32_16x16x32_bf16 v[44:47], v[118:121], v[174:177], v[44:47]
	v_mfma_f32_16x16x32_bf16 v[40:43], v[138:141], v[174:177], v[40:43]
	v_mfma_f32_16x16x32_bf16 v[28:31], v[118:121], v[182:185], v[28:31]
	v_mfma_f32_16x16x32_bf16 v[24:27], v[138:141], v[182:185], v[24:27]
	v_mfma_f32_16x16x32_bf16 v[12:15], v[118:121], v[206:209], v[12:15]
	v_mfma_f32_16x16x32_bf16 v[8:11], v[138:141], v[206:209], v[8:11]
	s_setprio 0
	s_setprio 1
	v_mfma_f32_16x16x32_bf16 v[52:55], v[146:149], v[162:165], v[52:55]
	v_mfma_f32_16x16x32_bf16 v[48:51], v[154:157], v[162:165], v[48:51]
	v_mfma_f32_16x16x32_bf16 v[36:39], v[146:149], v[170:173], v[36:39]
	v_mfma_f32_16x16x32_bf16 v[32:35], v[154:157], v[170:173], v[32:35]
	v_mfma_f32_16x16x32_bf16 v[20:23], v[146:149], v[178:181], v[20:23]
	v_mfma_f32_16x16x32_bf16 v[16:19], v[154:157], v[178:181], v[16:19]
	v_mfma_f32_16x16x32_bf16 v[4:7], v[146:149], v[202:205], v[4:7]
	v_mfma_f32_16x16x32_bf16 v[0:3], v[154:157], v[202:205], v[0:3]
	v_mfma_f32_16x16x32_bf16 v[52:55], v[150:153], v[166:169], v[52:55]
	v_mfma_f32_16x16x32_bf16 v[48:51], v[158:161], v[166:169], v[48:51]
	v_mfma_f32_16x16x32_bf16 v[36:39], v[150:153], v[174:177], v[36:39]
	v_mfma_f32_16x16x32_bf16 v[32:35], v[158:161], v[174:177], v[32:35]
	v_mfma_f32_16x16x32_bf16 v[20:23], v[150:153], v[182:185], v[20:23]
	v_mfma_f32_16x16x32_bf16 v[16:19], v[158:161], v[182:185], v[16:19]
	v_mfma_f32_16x16x32_bf16 v[4:7], v[150:153], v[206:209], v[4:7]
	v_mfma_f32_16x16x32_bf16 v[0:3], v[158:161], v[206:209], v[0:3]
	s_setprio 0
	s_barrier
	s_add_i32 s84, 0, 0x18000
	s_add_i32 s85, 0, 0x1c000
	v_add_u32_e32 v138, s84, v246
	v_add_u32_e32 v158, s85, v246
	ds_read_b128 v[114:117], v138
	ds_read_b128 v[118:121], v138 offset:1024
	ds_read_b128 v[130:133], v138 offset:2048
	ds_read_b128 v[138:141], v138 offset:3072
	ds_read_b128 v[146:149], v158
	ds_read_b128 v[150:153], v158 offset:1024
	ds_read_b128 v[154:157], v158 offset:2048
	ds_read_b128 v[158:161], v158 offset:3072
	s_add_u32 s48, s48, 0x100000
	s_addc_u32 s49, s49, 0
	s_mov_b32 m0, s19
	ds_read_b128 v[162:165], v251 offset:32768
	ds_read_b128 v[166:169], v251 offset:33792
	ds_read_b128 v[170:173], v251 offset:34816
	ds_read_b128 v[174:177], v251 offset:35840
	ds_read_b128 v[178:181], v251 offset:36864
	ds_read_b128 v[182:185], v251 offset:37888
	ds_read_b128 v[202:205], v251 offset:38912
	ds_read_b128 v[206:209], v251 offset:39936
	global_load_lds_dwordx4 v190, s[48:49]
	s_mov_b32 m0, s61
	s_nop 0
	global_load_lds_dwordx4 v194, s[48:49]
	s_waitcnt vmcnt(8)
	s_waitcnt lgkmcnt(0)
	s_barrier
	s_setprio 1
	s_waitcnt lgkmcnt(0)
	v_mfma_f32_16x16x32_bf16 v[126:129], v[114:117], v[162:165], v[126:129]
	v_mfma_f32_16x16x32_bf16 v[122:125], v[130:133], v[162:165], v[122:125]
	v_mfma_f32_16x16x32_bf16 v[110:113], v[114:117], v[170:173], v[110:113]
	v_mfma_f32_16x16x32_bf16 v[106:109], v[130:133], v[170:173], v[106:109]
	v_mfma_f32_16x16x32_bf16 v[94:97], v[114:117], v[178:181], v[94:97]
	v_mfma_f32_16x16x32_bf16 v[90:93], v[130:133], v[178:181], v[90:93]
	v_mfma_f32_16x16x32_bf16 v[78:81], v[114:117], v[202:205], v[78:81]
	v_mfma_f32_16x16x32_bf16 v[74:77], v[130:133], v[202:205], v[74:77]
	v_mfma_f32_16x16x32_bf16 v[126:129], v[118:121], v[166:169], v[126:129]
	v_mfma_f32_16x16x32_bf16 v[122:125], v[138:141], v[166:169], v[122:125]
	v_mfma_f32_16x16x32_bf16 v[110:113], v[118:121], v[174:177], v[110:113]
	v_mfma_f32_16x16x32_bf16 v[106:109], v[138:141], v[174:177], v[106:109]
	v_mfma_f32_16x16x32_bf16 v[94:97], v[118:121], v[182:185], v[94:97]
	v_mfma_f32_16x16x32_bf16 v[90:93], v[138:141], v[182:185], v[90:93]
	v_mfma_f32_16x16x32_bf16 v[78:81], v[118:121], v[206:209], v[78:81]
	v_mfma_f32_16x16x32_bf16 v[74:77], v[138:141], v[206:209], v[74:77]
	s_setprio 0
	s_setprio 1
	v_mfma_f32_16x16x32_bf16 v[142:145], v[146:149], v[162:165], v[142:145]
	v_mfma_f32_16x16x32_bf16 v[134:137], v[154:157], v[162:165], v[134:137]
	v_mfma_f32_16x16x32_bf16 v[102:105], v[146:149], v[170:173], v[102:105]
	v_mfma_f32_16x16x32_bf16 v[98:101], v[154:157], v[170:173], v[98:101]
	v_mfma_f32_16x16x32_bf16 v[86:89], v[146:149], v[178:181], v[86:89]
	v_mfma_f32_16x16x32_bf16 v[82:85], v[154:157], v[178:181], v[82:85]
	v_mfma_f32_16x16x32_bf16 v[70:73], v[146:149], v[202:205], v[70:73]
	v_mfma_f32_16x16x32_bf16 v[66:69], v[154:157], v[202:205], v[66:69]
	v_mfma_f32_16x16x32_bf16 v[142:145], v[150:153], v[166:169], v[142:145]
	v_mfma_f32_16x16x32_bf16 v[134:137], v[158:161], v[166:169], v[134:137]
	v_mfma_f32_16x16x32_bf16 v[102:105], v[150:153], v[174:177], v[102:105]
	v_mfma_f32_16x16x32_bf16 v[98:101], v[158:161], v[174:177], v[98:101]
	v_mfma_f32_16x16x32_bf16 v[86:89], v[150:153], v[182:185], v[86:89]
	v_mfma_f32_16x16x32_bf16 v[82:85], v[158:161], v[182:185], v[82:85]
	v_mfma_f32_16x16x32_bf16 v[70:73], v[150:153], v[206:209], v[70:73]
	v_mfma_f32_16x16x32_bf16 v[66:69], v[158:161], v[206:209], v[66:69]
	s_setprio 0
	s_barrier
	s_add_i32 s48, s84, s10
	v_lshl_add_u64 v[210:211], v[210:211], 0, s[16:17]
	s_mov_b32 m0, s48
	ds_read_b128 v[162:165], v251 offset:49152
	ds_read_b128 v[166:169], v251 offset:50176
	ds_read_b128 v[170:173], v251 offset:51200
	ds_read_b128 v[174:177], v251 offset:52224
	ds_read_b128 v[178:181], v251 offset:53248
	ds_read_b128 v[182:185], v251 offset:54272
	ds_read_b128 v[202:205], v251 offset:55296
	ds_read_b128 v[206:209], v251 offset:56320
	global_load_lds_dwordx4 v[210:211], off
	s_add_i32 m0, s48, 0x2000
	s_add_u32 s30, s30, 0x100080
	v_lshl_add_u64 v[210:211], v[212:213], 0, s[16:17]
	s_addc_u32 s31, s31, 0
	s_add_i32 s48, s85, s10
	global_load_lds_dwordx4 v[210:211], off
	s_mov_b32 m0, s48
	s_nop 0
	global_load_lds_dwordx4 v192, s[30:31]
	s_add_i32 m0, s48, 0x2000
	s_nop 0
	global_load_lds_dwordx4 v196, s[30:31]
	v_lshl_add_u64 v[210:211], v[214:215], 0, s[16:17]
	s_mov_b32 m0, s76
	s_nop 0
	global_load_lds_dwordx4 v[210:211], off
	v_lshl_add_u64 v[210:211], v[216:217], 0, s[16:17]
	s_mov_b32 m0, s77
	s_nop 0
	global_load_lds_dwordx4 v[210:211], off
	s_waitcnt vmcnt(8)
	s_waitcnt lgkmcnt(0)
	s_barrier
	s_setprio 1
	s_waitcnt lgkmcnt(0)
	v_mfma_f32_16x16x32_bf16 v[60:63], v[114:117], v[162:165], v[60:63]
	v_mfma_f32_16x16x32_bf16 v[56:59], v[130:133], v[162:165], v[56:59]
	v_mfma_f32_16x16x32_bf16 v[44:47], v[114:117], v[170:173], v[44:47]
	v_mfma_f32_16x16x32_bf16 v[40:43], v[130:133], v[170:173], v[40:43]
	v_mfma_f32_16x16x32_bf16 v[28:31], v[114:117], v[178:181], v[28:31]
	v_mfma_f32_16x16x32_bf16 v[24:27], v[130:133], v[178:181], v[24:27]
	v_mfma_f32_16x16x32_bf16 v[12:15], v[114:117], v[202:205], v[12:15]
	v_mfma_f32_16x16x32_bf16 v[8:11], v[130:133], v[202:205], v[8:11]
	v_mfma_f32_16x16x32_bf16 v[60:63], v[118:121], v[166:169], v[60:63]
	v_mfma_f32_16x16x32_bf16 v[56:59], v[138:141], v[166:169], v[56:59]
	v_mfma_f32_16x16x32_bf16 v[44:47], v[118:121], v[174:177], v[44:47]
	v_mfma_f32_16x16x32_bf16 v[40:43], v[138:141], v[174:177], v[40:43]
	v_mfma_f32_16x16x32_bf16 v[28:31], v[118:121], v[182:185], v[28:31]
	v_mfma_f32_16x16x32_bf16 v[24:27], v[138:141], v[182:185], v[24:27]
	v_mfma_f32_16x16x32_bf16 v[12:15], v[118:121], v[206:209], v[12:15]
	v_mfma_f32_16x16x32_bf16 v[8:11], v[138:141], v[206:209], v[8:11]
	s_setprio 0
	s_setprio 1
	v_mfma_f32_16x16x32_bf16 v[52:55], v[146:149], v[162:165], v[52:55]
	v_mfma_f32_16x16x32_bf16 v[48:51], v[154:157], v[162:165], v[48:51]
	v_mfma_f32_16x16x32_bf16 v[36:39], v[146:149], v[170:173], v[36:39]
	v_mfma_f32_16x16x32_bf16 v[32:35], v[154:157], v[170:173], v[32:35]
	v_mfma_f32_16x16x32_bf16 v[20:23], v[146:149], v[178:181], v[20:23]
	v_mfma_f32_16x16x32_bf16 v[16:19], v[154:157], v[178:181], v[16:19]
	v_mfma_f32_16x16x32_bf16 v[4:7], v[146:149], v[202:205], v[4:7]
	v_mfma_f32_16x16x32_bf16 v[0:3], v[154:157], v[202:205], v[0:3]
	v_mfma_f32_16x16x32_bf16 v[52:55], v[150:153], v[166:169], v[52:55]
	v_mfma_f32_16x16x32_bf16 v[48:51], v[158:161], v[166:169], v[48:51]
	v_mfma_f32_16x16x32_bf16 v[36:39], v[150:153], v[174:177], v[36:39]
	v_mfma_f32_16x16x32_bf16 v[32:35], v[158:161], v[174:177], v[32:35]
	v_mfma_f32_16x16x32_bf16 v[20:23], v[150:153], v[182:185], v[20:23]
	v_mfma_f32_16x16x32_bf16 v[16:19], v[158:161], v[182:185], v[16:19]
	v_mfma_f32_16x16x32_bf16 v[4:7], v[150:153], v[206:209], v[4:7]
	v_mfma_f32_16x16x32_bf16 v[0:3], v[158:161], v[206:209], v[0:3]
	s_setprio 0
	s_barrier
	s_add_i32 s91, s91, 2
	s_add_u32 s28, s28, 0x100
	s_addc_u32 s29, s29, 0
	s_add_u32 s82, s82, 0x100
	s_addc_u32 s83, s83, 0
	s_cmp_gt_u32 s91, 61
	s_cbranch_scc0 .LBB0_1461
	s_and_b64 vcc, exec, s[64:65]
	s_cbranch_vccz .LBB0_1464
	s_barrier

.LBB0_1532:
	s_add_u32 s30, s28, 0xfff00080
	s_addc_u32 s31, s29, -1
	s_add_i32 s73, 0, 0x10000
	s_cmp_eq_u32 s72, 60
	s_cselect_b32 s67, s49, s31
	s_cselect_b32 s66, s68, s30
	s_cselect_b32 s31, s47, s71
	s_cselect_b32 s30, s69, s70
	s_add_i32 s75, 0, 0x14000
	v_add_u32_e32 v110, s73, v223
	v_add_u32_e32 v170, s75, v223
	ds_read_b128 v[98:101], v110
	ds_read_b128 v[102:105], v110 offset:1024
	ds_read_b128 v[106:109], v110 offset:2048
	ds_read_b128 v[110:113], v110 offset:3072
	ds_read_b128 v[146:149], v170
	ds_read_b128 v[162:165], v170 offset:1024
	ds_read_b128 v[166:169], v170 offset:2048
	ds_read_b128 v[170:173], v170 offset:3072
	s_add_i32 m0, s1, 0xc000
	ds_read_b128 v[174:177], v225
	ds_read_b128 v[178:181], v225 offset:1024
	ds_read_b128 v[182:185], v225 offset:2048
	ds_read_b128 v[190:193], v225 offset:3072
	ds_read_b128 v[194:197], v225 offset:4096
	ds_read_b128 v[198:201], v225 offset:5120
	ds_read_b128 v[202:205], v225 offset:6144
	ds_read_b128 v[206:209], v225 offset:7168
	global_load_lds_dwordx4 v158, s[28:29]
	s_add_i32 m0, s1, 0xe000
	s_nop 0
	global_load_lds_dwordx4 v160, s[28:29]
	s_waitcnt vmcnt(8)
	s_waitcnt lgkmcnt(0)
	s_barrier
	s_setprio 1
	s_waitcnt lgkmcnt(0)
	v_mfma_f32_16x16x32_bf16 v[142:145], v[98:101], v[174:177], v[142:145]
	v_mfma_f32_16x16x32_bf16 v[138:141], v[106:109], v[174:177], v[138:141]
	v_mfma_f32_16x16x32_bf16 v[134:137], v[98:101], v[182:185], v[134:137]
	v_mfma_f32_16x16x32_bf16 v[130:133], v[106:109], v[182:185], v[130:133]
	v_mfma_f32_16x16x32_bf16 v[126:129], v[98:101], v[194:197], v[126:129]
	v_mfma_f32_16x16x32_bf16 v[122:125], v[106:109], v[194:197], v[122:125]
	v_mfma_f32_16x16x32_bf16 v[118:121], v[98:101], v[202:205], v[118:121]
	v_mfma_f32_16x16x32_bf16 v[114:117], v[106:109], v[202:205], v[114:117]
	v_mfma_f32_16x16x32_bf16 v[142:145], v[102:105], v[178:181], v[142:145]
	v_mfma_f32_16x16x32_bf16 v[138:141], v[110:113], v[178:181], v[138:141]
	v_mfma_f32_16x16x32_bf16 v[134:137], v[102:105], v[190:193], v[134:137]
	v_mfma_f32_16x16x32_bf16 v[130:133], v[110:113], v[190:193], v[130:133]
	v_mfma_f32_16x16x32_bf16 v[126:129], v[102:105], v[198:201], v[126:129]
	v_mfma_f32_16x16x32_bf16 v[122:125], v[110:113], v[198:201], v[122:125]
	v_mfma_f32_16x16x32_bf16 v[118:121], v[102:105], v[206:209], v[118:121]
	v_mfma_f32_16x16x32_bf16 v[114:117], v[110:113], v[206:209], v[114:117]
	s_setprio 0
	s_setprio 1
	v_mfma_f32_16x16x32_bf16 v[60:63], v[146:149], v[174:177], v[60:63]
	v_mfma_f32_16x16x32_bf16 v[56:59], v[166:169], v[174:177], v[56:59]
	v_mfma_f32_16x16x32_bf16 v[52:55], v[146:149], v[182:185], v[52:55]
	v_mfma_f32_16x16x32_bf16 v[48:51], v[166:169], v[182:185], v[48:51]
	v_mfma_f32_16x16x32_bf16 v[44:47], v[146:149], v[194:197], v[44:47]
	v_mfma_f32_16x16x32_bf16 v[40:43], v[166:169], v[194:197], v[40:43]
	v_mfma_f32_16x16x32_bf16 v[36:39], v[146:149], v[202:205], v[36:39]
	v_mfma_f32_16x16x32_bf16 v[32:35], v[166:169], v[202:205], v[32:35]
	v_mfma_f32_16x16x32_bf16 v[60:63], v[162:165], v[178:181], v[60:63]
	v_mfma_f32_16x16x32_bf16 v[56:59], v[170:173], v[178:181], v[56:59]
	v_mfma_f32_16x16x32_bf16 v[52:55], v[162:165], v[190:193], v[52:55]
	v_mfma_f32_16x16x32_bf16 v[48:51], v[170:173], v[190:193], v[48:51]
	v_mfma_f32_16x16x32_bf16 v[44:47], v[162:165], v[198:201], v[44:47]
	v_mfma_f32_16x16x32_bf16 v[40:43], v[170:173], v[198:201], v[40:43]
	v_mfma_f32_16x16x32_bf16 v[36:39], v[162:165], v[206:209], v[36:39]
	v_mfma_f32_16x16x32_bf16 v[32:35], v[170:173], v[206:209], v[32:35]
	s_setprio 0
	s_barrier
	s_add_i32 s73, s73, s0
	v_lshl_add_u64 v[210:211], s[30:31], 0, v[152:153]
	s_mov_b32 m0, s73
	ds_read_b128 v[174:177], v225 offset:16384
	ds_read_b128 v[178:181], v225 offset:17408
	ds_read_b128 v[182:185], v225 offset:18432
	ds_read_b128 v[190:193], v225 offset:19456
	ds_read_b128 v[194:197], v225 offset:20480
	ds_read_b128 v[198:201], v225 offset:21504
	ds_read_b128 v[202:205], v225 offset:22528
	ds_read_b128 v[206:209], v225 offset:23552
	global_load_lds_dwordx4 v152, s[30:31]
	s_add_i32 m0, s73, 0x2000
	s_add_u32 s82, s30, 0x100000
	v_lshl_add_u64 v[212:213], s[30:31], 0, v[156:157]
	s_addc_u32 s83, s31, 0
	s_add_i32 s73, s75, s0
	global_load_lds_dwordx4 v156, s[30:31]
	s_mov_b32 m0, s73
	v_lshl_add_u64 v[216:217], s[66:67], 0, v[154:155]
	global_load_lds_dwordx4 v152, s[82:83]
	s_add_i32 m0, s73, 0x2000
	s_nop 0
	global_load_lds_dwordx4 v156, s[82:83]
	v_lshl_add_u64 v[214:215], s[66:67], 0, v[150:151]
	s_mov_b32 m0, s1
	s_nop 0
	global_load_lds_dwordx4 v150, s[66:67]
	s_mov_b32 m0, s10
	s_nop 0
	global_load_lds_dwordx4 v154, s[66:67]
	s_waitcnt vmcnt(8)
	s_waitcnt lgkmcnt(0)
	s_barrier
	s_setprio 1
	s_waitcnt lgkmcnt(0)
	v_mfma_f32_16x16x32_bf16 v[94:97], v[98:101], v[174:177], v[94:97]
	v_mfma_f32_16x16x32_bf16 v[90:93], v[106:109], v[174:177], v[90:93]
	v_mfma_f32_16x16x32_bf16 v[86:89], v[98:101], v[182:185], v[86:89]
	v_mfma_f32_16x16x32_bf16 v[82:85], v[106:109], v[182:185], v[82:85]
	v_mfma_f32_16x16x32_bf16 v[78:81], v[98:101], v[194:197], v[78:81]
	v_mfma_f32_16x16x32_bf16 v[74:77], v[106:109], v[194:197], v[74:77]
	v_mfma_f32_16x16x32_bf16 v[70:73], v[98:101], v[202:205], v[70:73]
	v_mfma_f32_16x16x32_bf16 v[66:69], v[106:109], v[202:205], v[66:69]
	v_mfma_f32_16x16x32_bf16 v[94:97], v[102:105], v[178:181], v[94:97]
	v_mfma_f32_16x16x32_bf16 v[90:93], v[110:113], v[178:181], v[90:93]
	v_mfma_f32_16x16x32_bf16 v[86:89], v[102:105], v[190:193], v[86:89]
	v_mfma_f32_16x16x32_bf16 v[82:85], v[110:113], v[190:193], v[82:85]
	v_mfma_f32_16x16x32_bf16 v[78:81], v[102:105], v[198:201], v[78:81]
	v_mfma_f32_16x16x32_bf16 v[74:77], v[110:113], v[198:201], v[74:77]
	v_mfma_f32_16x16x32_bf16 v[70:73], v[102:105], v[206:209], v[70:73]
	v_mfma_f32_16x16x32_bf16 v[66:69], v[110:113], v[206:209], v[66:69]
	s_setprio 0
	s_setprio 1
	v_mfma_f32_16x16x32_bf16 v[28:31], v[146:149], v[174:177], v[28:31]
	v_mfma_f32_16x16x32_bf16 v[24:27], v[166:169], v[174:177], v[24:27]
	v_mfma_f32_16x16x32_bf16 v[20:23], v[146:149], v[182:185], v[20:23]
	v_mfma_f32_16x16x32_bf16 v[16:19], v[166:169], v[182:185], v[16:19]
	v_mfma_f32_16x16x32_bf16 v[12:15], v[146:149], v[194:197], v[12:15]
	v_mfma_f32_16x16x32_bf16 v[8:11], v[166:169], v[194:197], v[8:11]
	v_mfma_f32_16x16x32_bf16 v[4:7], v[146:149], v[202:205], v[4:7]
	v_mfma_f32_16x16x32_bf16 v[0:3], v[166:169], v[202:205], v[0:3]
	v_mfma_f32_16x16x32_bf16 v[28:31], v[162:165], v[178:181], v[28:31]
	v_mfma_f32_16x16x32_bf16 v[24:27], v[170:173], v[178:181], v[24:27]
	v_mfma_f32_16x16x32_bf16 v[20:23], v[162:165], v[190:193], v[20:23]
	v_mfma_f32_16x16x32_bf16 v[16:19], v[170:173], v[190:193], v[16:19]
	v_mfma_f32_16x16x32_bf16 v[12:15], v[162:165], v[198:201], v[12:15]
	v_mfma_f32_16x16x32_bf16 v[8:11], v[170:173], v[198:201], v[8:11]
	v_mfma_f32_16x16x32_bf16 v[4:7], v[162:165], v[206:209], v[4:7]
	v_mfma_f32_16x16x32_bf16 v[0:3], v[170:173], v[206:209], v[0:3]
	s_setprio 0
	s_barrier
	s_add_i32 s73, 0, 0x18000
	s_add_i32 s75, 0, 0x1c000
	v_add_u32_e32 v110, s73, v223
	v_add_u32_e32 v170, s75, v223
	ds_read_b128 v[98:101], v110
	ds_read_b128 v[102:105], v110 offset:1024
	ds_read_b128 v[106:109], v110 offset:2048
	ds_read_b128 v[110:113], v110 offset:3072
	ds_read_b128 v[146:149], v170
	ds_read_b128 v[162:165], v170 offset:1024
	ds_read_b128 v[166:169], v170 offset:2048
	ds_read_b128 v[170:173], v170 offset:3072
	s_add_u32 s66, s66, 0x100000
	s_addc_u32 s67, s67, 0
	s_mov_b32 m0, s11
	ds_read_b128 v[174:177], v225 offset:32768
	ds_read_b128 v[178:181], v225 offset:33792
	ds_read_b128 v[182:185], v225 offset:34816
	ds_read_b128 v[190:193], v225 offset:35840
	ds_read_b128 v[194:197], v225 offset:36864
	ds_read_b128 v[198:201], v225 offset:37888
	ds_read_b128 v[202:205], v225 offset:38912
	ds_read_b128 v[206:209], v225 offset:39936
	global_load_lds_dwordx4 v150, s[66:67]
	s_mov_b32 m0, s13
	s_nop 0
	global_load_lds_dwordx4 v154, s[66:67]
	s_waitcnt vmcnt(8)
	s_waitcnt lgkmcnt(0)
	s_barrier
	s_setprio 1
	s_waitcnt lgkmcnt(0)
	v_mfma_f32_16x16x32_bf16 v[142:145], v[98:101], v[174:177], v[142:145]
	v_mfma_f32_16x16x32_bf16 v[138:141], v[106:109], v[174:177], v[138:141]
	v_mfma_f32_16x16x32_bf16 v[134:137], v[98:101], v[182:185], v[134:137]
	v_mfma_f32_16x16x32_bf16 v[130:133], v[106:109], v[182:185], v[130:133]
	v_mfma_f32_16x16x32_bf16 v[126:129], v[98:101], v[194:197], v[126:129]
	v_mfma_f32_16x16x32_bf16 v[122:125], v[106:109], v[194:197], v[122:125]
	v_mfma_f32_16x16x32_bf16 v[118:121], v[98:101], v[202:205], v[118:121]
	v_mfma_f32_16x16x32_bf16 v[114:117], v[106:109], v[202:205], v[114:117]
	v_mfma_f32_16x16x32_bf16 v[142:145], v[102:105], v[178:181], v[142:145]
	v_mfma_f32_16x16x32_bf16 v[138:141], v[110:113], v[178:181], v[138:141]
	v_mfma_f32_16x16x32_bf16 v[134:137], v[102:105], v[190:193], v[134:137]
	v_mfma_f32_16x16x32_bf16 v[130:133], v[110:113], v[190:193], v[130:133]
	v_mfma_f32_16x16x32_bf16 v[126:129], v[102:105], v[198:201], v[126:129]
	v_mfma_f32_16x16x32_bf16 v[122:125], v[110:113], v[198:201], v[122:125]
	v_mfma_f32_16x16x32_bf16 v[118:121], v[102:105], v[206:209], v[118:121]
	v_mfma_f32_16x16x32_bf16 v[114:117], v[110:113], v[206:209], v[114:117]
	s_setprio 0
	s_setprio 1
	v_mfma_f32_16x16x32_bf16 v[60:63], v[146:149], v[174:177], v[60:63]
	v_mfma_f32_16x16x32_bf16 v[56:59], v[166:169], v[174:177], v[56:59]
	v_mfma_f32_16x16x32_bf16 v[52:55], v[146:149], v[182:185], v[52:55]
	v_mfma_f32_16x16x32_bf16 v[48:51], v[166:169], v[182:185], v[48:51]
	v_mfma_f32_16x16x32_bf16 v[44:47], v[146:149], v[194:197], v[44:47]
	v_mfma_f32_16x16x32_bf16 v[40:43], v[166:169], v[194:197], v[40:43]
	v_mfma_f32_16x16x32_bf16 v[36:39], v[146:149], v[202:205], v[36:39]
	v_mfma_f32_16x16x32_bf16 v[32:35], v[166:169], v[202:205], v[32:35]
	v_mfma_f32_16x16x32_bf16 v[60:63], v[162:165], v[178:181], v[60:63]
	v_mfma_f32_16x16x32_bf16 v[56:59], v[170:173], v[178:181], v[56:59]
	v_mfma_f32_16x16x32_bf16 v[52:55], v[162:165], v[190:193], v[52:55]
	v_mfma_f32_16x16x32_bf16 v[48:51], v[170:173], v[190:193], v[48:51]
	v_mfma_f32_16x16x32_bf16 v[44:47], v[162:165], v[198:201], v[44:47]
	v_mfma_f32_16x16x32_bf16 v[40:43], v[170:173], v[198:201], v[40:43]
	v_mfma_f32_16x16x32_bf16 v[36:39], v[162:165], v[206:209], v[36:39]
	v_mfma_f32_16x16x32_bf16 v[32:35], v[170:173], v[206:209], v[32:35]
	s_setprio 0
	s_barrier
	s_add_i32 s66, s73, s0
	v_lshl_add_u64 v[210:211], v[210:211], 0, s[16:17]
	s_mov_b32 m0, s66
	ds_read_b128 v[174:177], v225 offset:49152
	ds_read_b128 v[178:181], v225 offset:50176
	ds_read_b128 v[182:185], v225 offset:51200
	ds_read_b128 v[190:193], v225 offset:52224
	ds_read_b128 v[194:197], v225 offset:53248
	ds_read_b128 v[198:201], v225 offset:54272
	ds_read_b128 v[202:205], v225 offset:55296
	ds_read_b128 v[206:209], v225 offset:56320
	global_load_lds_dwordx4 v[210:211], off
	s_add_i32 m0, s66, 0x2000
	s_add_u32 s30, s30, 0x100080
	v_lshl_add_u64 v[210:211], v[212:213], 0, s[16:17]
	s_addc_u32 s31, s31, 0
	s_add_i32 s66, s75, s0
	global_load_lds_dwordx4 v[210:211], off
	s_mov_b32 m0, s66
	s_nop 0
	global_load_lds_dwordx4 v152, s[30:31]
	s_add_i32 m0, s66, 0x2000
	s_nop 0
	global_load_lds_dwordx4 v156, s[30:31]
	v_lshl_add_u64 v[210:211], v[214:215], 0, s[16:17]
	s_mov_b32 m0, s4
	s_nop 0
	global_load_lds_dwordx4 v[210:211], off
	v_lshl_add_u64 v[210:211], v[216:217], 0, s[16:17]
	s_mov_b32 m0, s90
	s_nop 0
	global_load_lds_dwordx4 v[210:211], off
	s_waitcnt vmcnt(8)
	s_waitcnt lgkmcnt(0)
	s_barrier
	s_setprio 1
	s_waitcnt lgkmcnt(0)
	v_mfma_f32_16x16x32_bf16 v[94:97], v[98:101], v[174:177], v[94:97]
	v_mfma_f32_16x16x32_bf16 v[90:93], v[106:109], v[174:177], v[90:93]
	v_mfma_f32_16x16x32_bf16 v[86:89], v[98:101], v[182:185], v[86:89]
	v_mfma_f32_16x16x32_bf16 v[82:85], v[106:109], v[182:185], v[82:85]
	v_mfma_f32_16x16x32_bf16 v[78:81], v[98:101], v[194:197], v[78:81]
	v_mfma_f32_16x16x32_bf16 v[74:77], v[106:109], v[194:197], v[74:77]
	v_mfma_f32_16x16x32_bf16 v[70:73], v[98:101], v[202:205], v[70:73]
	v_mfma_f32_16x16x32_bf16 v[66:69], v[106:109], v[202:205], v[66:69]
	v_mfma_f32_16x16x32_bf16 v[94:97], v[102:105], v[178:181], v[94:97]
	v_mfma_f32_16x16x32_bf16 v[90:93], v[110:113], v[178:181], v[90:93]
	v_mfma_f32_16x16x32_bf16 v[86:89], v[102:105], v[190:193], v[86:89]
	v_mfma_f32_16x16x32_bf16 v[82:85], v[110:113], v[190:193], v[82:85]
	v_mfma_f32_16x16x32_bf16 v[78:81], v[102:105], v[198:201], v[78:81]
	v_mfma_f32_16x16x32_bf16 v[74:77], v[110:113], v[198:201], v[74:77]
	v_mfma_f32_16x16x32_bf16 v[70:73], v[102:105], v[206:209], v[70:73]
	v_mfma_f32_16x16x32_bf16 v[66:69], v[110:113], v[206:209], v[66:69]
	s_setprio 0
	s_setprio 1
	v_mfma_f32_16x16x32_bf16 v[28:31], v[146:149], v[174:177], v[28:31]
	v_mfma_f32_16x16x32_bf16 v[24:27], v[166:169], v[174:177], v[24:27]
	v_mfma_f32_16x16x32_bf16 v[20:23], v[146:149], v[182:185], v[20:23]
	v_mfma_f32_16x16x32_bf16 v[16:19], v[166:169], v[182:185], v[16:19]
	v_mfma_f32_16x16x32_bf16 v[12:15], v[146:149], v[194:197], v[12:15]
	v_mfma_f32_16x16x32_bf16 v[8:11], v[166:169], v[194:197], v[8:11]
	v_mfma_f32_16x16x32_bf16 v[4:7], v[146:149], v[202:205], v[4:7]
	v_mfma_f32_16x16x32_bf16 v[0:3], v[166:169], v[202:205], v[0:3]
	v_mfma_f32_16x16x32_bf16 v[28:31], v[162:165], v[178:181], v[28:31]
	v_mfma_f32_16x16x32_bf16 v[24:27], v[170:173], v[178:181], v[24:27]
	v_mfma_f32_16x16x32_bf16 v[20:23], v[162:165], v[190:193], v[20:23]
	v_mfma_f32_16x16x32_bf16 v[16:19], v[170:173], v[190:193], v[16:19]
	v_mfma_f32_16x16x32_bf16 v[12:15], v[162:165], v[198:201], v[12:15]
	v_mfma_f32_16x16x32_bf16 v[8:11], v[170:173], v[198:201], v[8:11]
	v_mfma_f32_16x16x32_bf16 v[4:7], v[162:165], v[206:209], v[4:7]
	v_mfma_f32_16x16x32_bf16 v[0:3], v[170:173], v[206:209], v[0:3]
	s_setprio 0
	s_barrier
	s_add_i32 s72, s72, 2
	s_add_u32 s28, s28, 0x100
	s_addc_u32 s29, s29, 0
	s_add_u32 s70, s70, 0x100
	s_addc_u32 s71, s71, 0
	s_cmp_gt_u32 s72, 61
	s_cbranch_scc0 .LBB0_1532
	s_and_b64 vcc, exec, s[44:45]
	s_cbranch_vccz .LBB0_1535
	s_barrier
